# phases D and E: per-tile HBM side loads (gates / residual rows) issued after the first K-slice LDS-DMA loads, pre-loop wait counted so only the K slice is awaited
# speedup vs baseline: 1.0049x; 1.0043x over previous
; DI void gemm_tile(const bf16_t* __restrict__ A, int lda, const bf16_t* __restrict__ Bt, int ldb, int bvalid, int K, f32x4 (&acc)[4][4], char* lds, bool preloaded = false) {
;     ...
;   const bf16_t* ap = A + (size_t)lr * lda + ((lc ^ ((lr >> 1) & 7)) << 3);
;   const bf16_t* bp = Bt + ((lc ^ ((lr >> 1) & 7)) << 3);
;   typedef __attribute__((address_space(1))) const unsigned gptr_t;
;   typedef __attribute__((address_space(3))) unsigned lptr_t;
;   const unsigned lbase = (unsigned)(size_t)lds + (unsigned)tid * 16u;
; DI void phaseE_tile(const P& p, int layer, int mt, int nt, char* lds) {
;     ...
;   const int col = col0 + wn * 64 + fr * 4;
;   f32x4 xr[16];
; #pragma unroll
;   for (int ps = 0; ps < 16; ++ps) {
;     const int row = row0 + ps * 8 + wm * 4 + fq;
;     const float* xin = (layer == 0) ? ((row < NTP) ? p.x_p + (size_t)row * DM : p.x_s + (size_t)(row - NTP) * DM) : XF + (size_t)row * DM;
;     xr[ps] = __builtin_nontemporal_load((const f32x4*)(xin + col));
;   }
;   gemm_tile((const bf16_t*)(p.ws + W_MERGED) + (size_t)row0 * LDX, LDX, (const bf16_t*)(p.ws + W_WO) + ((size_t)layer * 1024 + col0) * LDX, LDX, 128, 1024, acc, lds);
.Lxr_go:
	s_add_i32 s8, s8, s11
	s_lshl_b32 s9, s8, 12
	v_lshlrev_b32_e32 v242, 12, v142
	s_add_u32 s36, s36, s9
	s_addc_u32 s37, s37, 0
	v_lshl_add_u32 v242, v130, 2, v242
.LBB0_169:
	s_mul_i32 s8, s10, 0x880
	s_mul_hi_i32 s9, s10, 0x880
	s_add_u32 s24, s58, s8
	s_addc_u32 s25, s59, s9
	s_ashr_i32 s23, s22, 31
	s_add_u32 s26, s4, s22
	s_addc_u32 s23, s5, s23
	v_mov_b32_e32 v76, v158
	s_mulk_i32 s23, 0x880
	s_mul_hi_u32 s27, s26, 0x880
	s_add_i32 s27, s27, s23
	v_lshrrev_b32_e32 v78, 4, v76
	s_mulk_i32 s26, 0x880
	v_readlane_b32 s28, v240, 31
	v_xor_b32_e32 v0, v78, v76
	v_readlane_b32 s29, v240, 32
	s_add_u32 s26, s28, s26
	v_ashrrev_i32_e32 v77, 3, v76
	v_mov_b64_e32 v[66:67], s[24:25]
	s_movk_i32 s28, 0x880
	v_lshlrev_b32_e32 v0, 4, v0
	s_addc_u32 s27, s29, s27
	v_mad_i64_i32 v[66:67], s[24:25], v77, s28, v[66:67]
	v_and_b32_e32 v0, 0x70, v0
	v_lshl_add_u64 v[66:67], v[66:67], 0, v[0:1]
	v_lshl_add_u64 v[68:69], s[26:27], 0, v[0:1]
	v_lshlrev_b32_e32 v145, 4, v76
	v_and_b32_e32 v0, 0x7f, v77
	v_add_u32_e32 v72, 0x4000, v145
	v_readfirstlane_b32 s24, v145
	v_mul_u32_u24_e32 v0, 0x440, v0
	s_mov_b32 m0, s24
	v_lshlrev_b32_e32 v0, 1, v0
	v_readfirstlane_b32 s24, v72
	global_load_lds_dwordx4 v[66:67], off
	v_lshl_add_u64 v[70:71], v[68:69], 0, v[0:1]
	s_mov_b32 m0, s24
	s_mov_b64 s[24:25], 0x11000
	v_add_u32_e32 v72, 0x1000, v145
	global_load_lds_dwordx4 v[70:71], off
	v_lshl_add_u64 v[70:71], v[66:67], 0, s[24:25]
	v_readfirstlane_b32 s24, v72
	s_mov_b32 m0, s24
	v_add_u32_e32 v74, 0x5000, v145
	global_load_lds_dwordx4 v[70:71], off
	v_add_u32_e32 v70, 32, v77
	v_and_b32_e32 v70, 0x7f, v70
	v_mul_u32_u24_e32 v70, 0x440, v70
	v_lshlrev_b32_e32 v70, 1, v70
	v_mov_b32_e32 v71, v1
	v_readfirstlane_b32 s24, v74
	v_lshl_add_u64 v[72:73], v[68:69], 0, v[70:71]
	s_mov_b32 m0, s24
	s_mov_b64 s[24:25], 0x22000
	v_add_u32_e32 v74, 0x2000, v145
	global_load_lds_dwordx4 v[72:73], off
	v_lshl_add_u64 v[72:73], v[66:67], 0, s[24:25]
	v_readfirstlane_b32 s24, v74
	s_mov_b32 m0, s24
	v_add_u32_e32 v82, 0x6000, v145
	global_load_lds_dwordx4 v[72:73], off
	v_bitop3_b32 v72, v77, 64, v166 bitop3:0x6c
	v_mul_u32_u24_e32 v72, 0x440, v72
	v_lshlrev_b32_e32 v72, 1, v72
	v_mov_b32_e32 v73, v1
	v_readfirstlane_b32 s24, v82
	v_lshl_add_u64 v[74:75], v[68:69], 0, v[72:73]
	s_mov_b32 m0, s24
	s_mov_b64 s[24:25], 0x33000
	global_load_lds_dwordx4 v[74:75], off
	v_add_u32_e32 v74, 0x3000, v145
	v_lshl_add_u64 v[66:67], v[66:67], 0, s[24:25]
	v_readfirstlane_b32 s24, v74
	s_mov_b32 m0, s24
	v_add_u32_e32 v74, 0x7000, v145
	global_load_lds_dwordx4 v[66:67], off
	v_add_u32_e32 v66, 0x60, v77
	v_and_b32_e32 v66, 0x7f, v66
	v_mul_u32_u24_e32 v66, 0x440, v66
	v_lshlrev_b32_e32 v66, 1, v66
	v_mov_b32_e32 v67, v1
	v_readfirstlane_b32 s24, v74
	v_lshl_add_u64 v[68:69], v[68:69], 0, v[66:67]
	s_mov_b32 m0, s24
	v_readfirstlane_b32 s23, v76
	global_load_lds_dwordx4 v[68:69], off
	global_load_dwordx4 v[2:5], v242, s[36:37] nt
	s_add_u32 s36, s36, 0x8000
	s_addc_u32 s37, s37, 0
	global_load_dwordx4 v[6:9], v242, s[36:37] nt
	s_add_u32 s36, s36, 0x8000
	s_addc_u32 s37, s37, 0
	global_load_dwordx4 v[10:13], v242, s[36:37] nt
	s_add_u32 s36, s36, 0x8000
	s_addc_u32 s37, s37, 0
	global_load_dwordx4 v[14:17], v242, s[36:37] nt
	s_add_u32 s36, s36, 0x8000
	s_addc_u32 s37, s37, 0
	global_load_dwordx4 v[18:21], v242, s[36:37] nt
	s_add_u32 s36, s36, 0x8000
	s_addc_u32 s37, s37, 0
	global_load_dwordx4 v[22:25], v242, s[36:37] nt
	s_add_u32 s36, s36, 0x8000
	s_addc_u32 s37, s37, 0
	global_load_dwordx4 v[26:29], v242, s[36:37] nt
	s_add_u32 s36, s36, 0x8000
	s_addc_u32 s37, s37, 0
	global_load_dwordx4 v[30:33], v242, s[36:37] nt
; DI void gemm_tile(const bf16_t* __restrict__ A, int lda, const bf16_t* __restrict__ Bt, int ldb, int bvalid, int K, f32x4 (&acc)[4][4], char* lds, bool preloaded = false) {
;     ...
;   if (!preloaded) { GLDS(0, 0) }
;   __syncthreads();
; DI void phaseE_tile(const P& p, int layer, int mt, int nt, char* lds) {
;     ...
;   f32x4 xr[16];
; #pragma unroll
;   for (int ps = 0; ps < 16; ++ps) {
;     const int row = row0 + ps * 8 + wm * 4 + fq;
;     const float* xin = (layer == 0) ? ((row < NTP) ? p.x_p + (size_t)row * DM : p.x_s + (size_t)(row - NTP) * DM) : XF + (size_t)row * DM;
;     xr[ps] = __builtin_nontemporal_load((const f32x4*)(xin + col));
;   }
;   gemm_tile((const bf16_t*)(p.ws + W_MERGED) + (size_t)row0 * LDX, LDX, (const bf16_t*)(p.ws + W_WO) + ((size_t)layer * 1024 + col0) * LDX, LDX, 128, 1024, acc, lds);
	s_add_u32 s36, s36, 0x8000
	s_addc_u32 s37, s37, 0
	global_load_dwordx4 v[34:37], v242, s[36:37] nt
	s_add_u32 s36, s36, 0x8000
	s_addc_u32 s37, s37, 0
	global_load_dwordx4 v[38:41], v242, s[36:37] nt
	s_add_u32 s36, s36, 0x8000
	s_addc_u32 s37, s37, 0
	global_load_dwordx4 v[42:45], v242, s[36:37] nt
	s_add_u32 s36, s36, 0x8000
	s_addc_u32 s37, s37, 0
	global_load_dwordx4 v[46:49], v242, s[36:37] nt
	s_add_u32 s36, s36, 0x8000
	s_addc_u32 s37, s37, 0
	global_load_dwordx4 v[50:53], v242, s[36:37] nt
	s_add_u32 s36, s36, 0x8000
	s_addc_u32 s37, s37, 0
	global_load_dwordx4 v[54:57], v242, s[36:37] nt
	s_add_u32 s36, s36, 0x8000
	s_addc_u32 s37, s37, 0
	global_load_dwordx4 v[58:61], v242, s[36:37] nt
	s_add_u32 s36, s36, 0x8000
	s_addc_u32 s37, s37, 0
	global_load_dwordx4 v[62:65], v242, s[36:37] nt
	s_lshl_b32 s24, s23, 7
	v_lshlrev_b32_e32 v68, 7, v76
	s_lshl_b32 s23, s23, 6
	v_bfe_u32 v79, v76, 4, 2
	v_lshrrev_b32_e32 v80, 1, v76
	v_bfe_u32 v81, v76, 1, 3
	s_and_b32 s24, s24, 0x2000
	v_and_b32_e32 v68, 0x780, v68
	s_and_b32 s23, s23, 0xffffe000
	v_or_b32_e32 v146, s24, v68
	v_bitop3_b32 v69, v80, v79, 7 bitop3:0x6c
	v_or_b32_e32 v148, s23, v68
	v_bitop3_b32 v68, v79, v81, 4 bitop3:0x36
	v_lshlrev_b32_e32 v149, 4, v69
	v_lshlrev_b32_e32 v147, 4, v68
	v_mov_b64_e32 v[68:69], s[8:9]
	v_bitop3_b32 v74, v78, 7, v76 bitop3:0x48
	v_mad_i64_i32 v[68:69], s[8:9], v77, s28, v[68:69]
	v_lshlrev_b32_e32 v74, 4, v74
	v_or_b32_e32 v68, v68, v74
	s_mul_hi_i32 s8, s22, 0x880
	s_mulk_i32 s22, 0x880
	v_lshl_add_u64 v[132:133], s[90:91], 0, v[68:69]
	v_or_b32_e32 v68, s22, v74
	v_mov_b32_e32 v69, s8
	v_lshl_add_u64 v[70:71], v[68:69], 0, v[70:71]
	v_lshl_add_u64 v[66:67], v[68:69], 0, v[66:67]
	v_lshl_add_u64 v[74:75], v[68:69], 0, v[0:1]
	v_lshl_add_u64 v[136:137], s[6:7], 0, v[70:71]
	v_lshl_add_u64 v[70:71], v[68:69], 0, v[72:73]
	v_lshl_add_u64 v[140:141], s[6:7], 0, v[66:67]
	v_mov_b32_e32 v66, 0
	v_lshl_add_u64 v[134:135], s[6:7], 0, v[74:75]
	v_lshl_add_u64 v[138:139], s[6:7], 0, v[70:71]
	s_mov_b64 s[8:9], 0
	s_mov_b32 s22, 0
	v_mov_b32_e32 v67, v66
	v_mov_b32_e32 v68, v66
	v_mov_b32_e32 v69, v66
	v_mov_b32_e32 v70, v66
	v_mov_b32_e32 v71, v66
	v_mov_b32_e32 v72, v66
	v_mov_b32_e32 v73, v66
	v_mov_b32_e32 v74, v66
	v_mov_b32_e32 v75, v66
	v_mov_b32_e32 v76, v66
	v_mov_b32_e32 v77, v66
	v_mov_b32_e32 v78, v66
	v_mov_b32_e32 v79, v66
	v_mov_b32_e32 v80, v66
	v_mov_b32_e32 v81, v66
	v_mov_b32_e32 v82, v66
	v_mov_b32_e32 v83, v66
	v_mov_b32_e32 v84, v66
	v_mov_b32_e32 v85, v66
	v_mov_b32_e32 v86, v66
	v_mov_b32_e32 v87, v66
	v_mov_b32_e32 v88, v66
	v_mov_b32_e32 v89, v66
	v_mov_b32_e32 v90, v66
	v_mov_b32_e32 v91, v66
	v_mov_b32_e32 v92, v66
	v_mov_b32_e32 v93, v66
	v_mov_b32_e32 v94, v66
	v_mov_b32_e32 v95, v66
	v_mov_b32_e32 v96, v66
	v_mov_b32_e32 v97, v66
	v_mov_b32_e32 v98, v66
	v_mov_b32_e32 v99, v66
	v_mov_b32_e32 v100, v66
	v_mov_b32_e32 v101, v66
	v_mov_b32_e32 v102, v66
	v_mov_b32_e32 v103, v66
	v_mov_b32_e32 v104, v66
	v_mov_b32_e32 v105, v66
	v_mov_b32_e32 v106, v66
	v_mov_b32_e32 v107, v66
	v_mov_b32_e32 v108, v66
	v_mov_b32_e32 v109, v66
	v_mov_b32_e32 v110, v66
	v_mov_b32_e32 v111, v66
	v_mov_b32_e32 v112, v66
	v_mov_b32_e32 v113, v66
	v_mov_b32_e32 v114, v66
	v_mov_b32_e32 v115, v66
	v_mov_b32_e32 v116, v66
	v_mov_b32_e32 v117, v66
	v_mov_b32_e32 v118, v66
	v_mov_b32_e32 v119, v66
	v_mov_b32_e32 v120, v66
	v_mov_b32_e32 v121, v66
	v_mov_b32_e32 v122, v66
	v_mov_b32_e32 v123, v66
	v_mov_b32_e32 v124, v66
	v_mov_b32_e32 v125, v66
	v_mov_b32_e32 v126, v66
	v_mov_b32_e32 v127, v66
	v_mov_b32_e32 v128, v66
	v_mov_b32_e32 v129, v66
	s_waitcnt vmcnt(16) lgkmcnt(0)
	s_barrier
	.p2alignl 6, 3212836864

; DI void gemm_tile(const bf16_t* __restrict__ A, int lda, const bf16_t* __restrict__ Bt, int ldb, int bvalid, int K, f32x4 (&acc)[4][4], char* lds, bool preloaded = false) {
;     ...
;   const bf16_t* ap = A + (size_t)lr * lda + ((lc ^ ((lr >> 1) & 7)) << 3);
;   const bf16_t* bp = Bt + ((lc ^ ((lr >> 1) & 7)) << 3);
;   typedef __attribute__((address_space(1))) const unsigned gptr_t;
;   typedef __attribute__((address_space(3))) unsigned lptr_t;
;   const unsigned lbase = (unsigned)(size_t)lds + (unsigned)tid * 16u;
; DI void phaseD_tile(const P& p, int layer, int mt, int nt, char* lds) {
;     ...
;   const size_t goff = ((size_t)((mt * 2 + wm) * 16 + nt * 2 + wn) * 64 + lane) * 16;
;   const unsigned* GP = (const unsigned*)(p.ws + W_GP) + goff;
;   const unsigned* GA = (const unsigned*)(p.ws + W_GA) + goff;
;   u32x4 gpv[4], gav[4];
; #pragma unroll
;   for (int mi = 0; mi < 4; ++mi) { gpv[mi] = __builtin_nontemporal_load((const u32x4*)(GP + mi * 4)); gav[mi] = __builtin_nontemporal_load((const u32x4*)(GA + mi * 4)); }
;   gemm_tile((const bf16_t*)(p.ws + W_POOLED) + (size_t)row0 * 512, 512, (const bf16_t*)(p.ws + W_WPO) + ((size_t)layer * 1024 + col0) * 512, 512, 128, 512, acc, lds);
;   gemm_prefetch0((const bf16_t*)(p.ws + W_ZA) + (size_t)row0 * 512, 512, (const bf16_t*)(p.ws + W_WAO) + ((size_t)layer * 1024 + col0) * 512, 512, 128, lds);
.LBB0_277:
	v_mov_b32_e32 v99, v158
	v_mov_b32_e32 v2, v158
	s_lshl_b32 s8, s6, 1
	v_readfirstlane_b32 s5, v2
	s_ashr_i32 s19, s5, 7
	s_bfe_u32 s20, s5, 0x10006
	s_lshl_b32 s5, s7, 5
	s_lshl_b32 s4, s7, 7
	s_lshl_b32 s7, s19, 4
	s_add_i32 s5, s8, s5
	s_add_i32 s5, s5, s7
	s_or_b32 s8, s5, s20
	s_ashr_i32 s9, s8, 31
	v_and_b32_e32 v0, 63, v99
	s_lshl_b64 s[8:9], s[8:9], 12
	v_lshl_or_b32 v2, v0, 6, s8
	v_mov_b32_e32 v3, s9
	v_readlane_b32 s8, v240, 41
	v_readlane_b32 s9, v240, 42
	s_ashr_i32 s5, s4, 31
	s_lshl_b32 s6, s6, 7
	v_lshl_add_u64 v[6:7], s[8:9], 0, v[2:3]
	v_readlane_b32 s8, v240, 43
	v_readlane_b32 s9, v240, 44
	v_mov_b32_e32 v30, v158
	v_readlane_b32 s22, v240, 35
	v_lshl_add_u64 v[10:11], s[8:9], 0, v[2:3]
	s_lshl_b64 s[8:9], s[4:5], 10
	s_add_u32 s10, s74, s8
	s_addc_u32 s11, s75, s9
	s_ashr_i32 s7, s6, 31
	s_lshl_b64 s[12:13], s[6:7], 9
	s_add_u32 s12, s12, s94
	s_nop 0
	v_mov_b64_e32 v[242:243], v[6:7]
	v_mov_b64_e32 v[244:245], v[10:11]
	s_addc_u32 s13, s13, s95
	s_lshl_b64 s[12:13], s[12:13], 1
	v_ashrrev_i32_e32 v12, 3, v30
	v_lshrrev_b32_e32 v0, 4, v30
	v_ashrrev_i32_e32 v13, 31, v12
	v_xor_b32_e32 v0, v0, v30
	v_readlane_b32 s23, v240, 36
	s_add_u32 s22, s22, s12
	v_lshlrev_b64 v[10:11], 10, v[12:13]
	v_lshlrev_b32_e32 v0, 4, v0
	s_addc_u32 s23, s23, s13
	v_lshl_add_u64 v[10:11], s[10:11], 0, v[10:11]
	v_and_b32_e32 v0, 0x70, v0
	v_lshlrev_b32_e32 v35, 9, v12
	v_lshl_add_u64 v[10:11], v[10:11], 0, v[0:1]
	v_lshl_add_u64 v[26:27], s[22:23], 0, v[0:1]
	v_and_b32_e32 v0, 0xfe00, v35
	v_lshlrev_b32_e32 v34, 4, v30
	v_lshlrev_b32_e32 v0, 1, v0
	v_add_u32_e32 v22, 0x4000, v34
	v_readfirstlane_b32 s5, v34
	v_lshl_add_u64 v[12:13], v[26:27], 0, v[0:1]
	v_add_u32_e32 v0, 0x1000, v34
	s_mov_b32 m0, s5
	v_readfirstlane_b32 s10, v22
	v_readfirstlane_b32 s11, v0
	v_add_u32_e32 v0, 0x4000, v35
	global_load_lds_dwordx4 v[10:11], off
	s_mov_b32 m0, s10
	s_mov_b64 s[40:41], 0x8000
	v_and_b32_e32 v0, 0xfe00, v0
	global_load_lds_dwordx4 v[12:13], off
	v_lshl_add_u64 v[22:23], v[10:11], 0, s[40:41]
	s_mov_b32 m0, s11
	v_lshlrev_b32_e32 v0, 1, v0
	global_load_lds_dwordx4 v[22:23], off
	v_lshl_add_u64 v[22:23], v[26:27], 0, v[0:1]
	v_add_u32_e32 v0, 0x5000, v34
	s_mov_b32 s33, 0x8000
	v_readfirstlane_b32 s21, v0
	v_add_u32_e32 v0, 0x2000, v34
	s_mov_b32 m0, s21
	s_mov_b64 s[42:43], 0x10000
	v_readfirstlane_b32 s22, v0
	v_bitop3_b32 v0, v35, s33, v167 bitop3:0x6c
	global_load_lds_dwordx4 v[22:23], off
	v_lshl_add_u64 v[24:25], v[10:11], 0, s[42:43]
	s_mov_b32 m0, s22
	v_lshlrev_b32_e32 v0, 1, v0
	global_load_lds_dwordx4 v[24:25], off
	v_lshl_add_u64 v[24:25], v[26:27], 0, v[0:1]
	v_add_u32_e32 v0, 0x6000, v34
	v_readfirstlane_b32 s26, v30
	v_readfirstlane_b32 s23, v0
	v_add_u32_e32 v0, 0x3000, v34
	s_lshl_b32 s27, s26, 7
	v_readfirstlane_b32 s24, v0
	v_add_u32_e32 v0, 0xc000, v35
	v_and_b32_e32 v0, 0xfe00, v0
	v_lshlrev_b32_e32 v0, 1, v0
	v_lshl_add_u64 v[26:27], v[26:27], 0, v[0:1]
	v_add_u32_e32 v0, 0x7000, v34
	s_lshl_b32 s26, s26, 6
	v_readfirstlane_b32 s25, v0
	v_lshlrev_b32_e32 v0, 7, v30
	v_bfe_u32 v31, v30, 4, 2
	v_bfe_u32 v33, v30, 1, 3
	s_mov_b32 m0, s23
	s_mov_b64 s[50:51], 0x18000
	s_and_b32 s27, s27, 0x2000
	v_and_b32_e32 v0, 0x780, v0
	s_and_b32 s26, s26, 0xffffe000
	v_lshrrev_b32_e32 v32, 1, v30
	global_load_lds_dwordx4 v[24:25], off
	v_lshl_add_u64 v[28:29], v[10:11], 0, s[50:51]
	s_mov_b32 m0, s24
	v_or_b32_e32 v30, s27, v0
	v_or_b32_e32 v37, s26, v0
	v_bitop3_b32 v0, v31, v33, 4 bitop3:0x36
	global_load_lds_dwordx4 v[28:29], off
	v_bitop3_b32 v28, v32, v31, 7 bitop3:0x6c
	v_lshlrev_b32_e32 v31, 4, v0
	v_add_u32_e32 v0, 0x8000, v34
	s_mov_b32 m0, s25
	s_mov_b64 s[38:39], 0x80
	v_add_u32_e32 v32, 0xc000, v34
	v_readfirstlane_b32 s29, v0
	global_load_lds_dwordx4 v[26:27], off
	v_lshlrev_b32_e32 v36, 4, v28
	v_lshl_add_u64 v[28:29], v[10:11], 0, s[38:39]
	s_mov_b32 m0, s29
	v_readfirstlane_b32 s26, v32
	v_add_u32_e32 v0, 0x9000, v34
	global_load_dwordx4 v[2:5], v[242:243], off offset:48 nt
	global_load_dwordx4 v[14:17], v[242:243], off offset:32 nt
	global_load_dwordx4 v[54:57], v[242:243], off offset:16 nt
	global_load_dwordx4 v[38:41], v[242:243], off nt
	global_load_dwordx4 v[6:9], v[244:245], off offset:48 nt
	global_load_dwordx4 v[18:21], v[244:245], off offset:32 nt
	global_load_dwordx4 v[58:61], v[244:245], off offset:16 nt
	global_load_dwordx4 v[46:49], v[244:245], off nt
	s_waitcnt vmcnt(8) lgkmcnt(0)
	s_barrier
; #define MFMA16(a, b, c) __builtin_amdgcn_mfma_f32_16x16x32_bf16((a), (b), (c), 0, 0, 0)
; DI void gemm_tile(const bf16_t* __restrict__ A, int lda, const bf16_t* __restrict__ Bt, int ldb, int bvalid, int K, f32x4 (&acc)[4][4], char* lds, bool preloaded = false) {
;     ...
;   auto compute = [&](int st) {
;     const char* base = lds + st * 32768;
;     bf16x8 af[2][4], bfr[2][4];
; #pragma unroll
;     for (int s = 0; s < 2; ++s) {
;       const int ch = ((4 * s + fq) ^ fx) << 4;
; #pragma unroll
;       for (int mi = 0; mi < 4; ++mi) af[s][mi] = *(const bf16x8*)(base + (wm * 64 + mi * 16 + fr) * 128 + ch);
; #pragma unroll
;       for (int ni = 0; ni < 4; ++ni) bfr[s][ni] = *(const bf16x8*)(base + 16384 + (wn * 64 + ni * 16 + fr) * 128 + ch);
;     }
;     __builtin_amdgcn_s_setprio(1);
; #pragma unroll
;     for (int s = 0; s < 2; ++s)
; #pragma unroll
;       for (int mi = 0; mi < 4; ++mi)
; #pragma unroll
;         for (int ni = 0; ni < 4; ++ni) acc[mi][ni] = MFMA16(af[s][mi], bfr[s][ni], acc[mi][ni]);
;     __builtin_amdgcn_s_setprio(0);
;   };
;   const int nk = K >> 6;
;   if (!preloaded) { GLDS(0, 0) }
;   __syncthreads();
;   for (int kt = 0; kt < nk; ++kt) {
;     if (kt + 1 < nk) { GLDS((kt + 1) & 1, (kt + 1) << 6) }
;     compute(kt & 1);
;     __syncthreads();
;   }
	global_load_lds_dwordx4 v[28:29], off
	v_lshl_add_u64 v[28:29], v[12:13], 0, s[38:39]
	s_mov_b32 m0, s26
	s_mov_b64 s[58:59], 0x8080
	v_readfirstlane_b32 s27, v0
	v_add_u32_e32 v0, 0xd000, v34
	global_load_lds_dwordx4 v[28:29], off
	v_lshl_add_u64 v[28:29], v[10:11], 0, s[58:59]
	s_mov_b32 m0, s27
	v_readfirstlane_b32 s28, v0
	v_add_u32_e32 v0, 0xa000, v34
	global_load_lds_dwordx4 v[28:29], off
	v_lshl_add_u64 v[28:29], v[22:23], 0, s[38:39]
	s_mov_b32 m0, s28
	s_mov_b64 s[62:63], 0x10080
	v_readfirstlane_b32 s30, v0
	v_add_u32_e32 v0, 0xe000, v34
	global_load_lds_dwordx4 v[28:29], off
	v_lshl_add_u64 v[28:29], v[10:11], 0, s[62:63]
	s_mov_b32 m0, s30
	v_readfirstlane_b32 s31, v0
	v_add_u32_e32 v0, 0xb000, v34
	global_load_lds_dwordx4 v[28:29], off
	v_lshl_add_u64 v[28:29], v[24:25], 0, s[38:39]
	s_mov_b32 m0, s31
	s_mov_b64 s[68:69], 0x18080
	v_readfirstlane_b32 s34, v0
	v_add_u32_e32 v0, 0xf000, v34
	global_load_lds_dwordx4 v[28:29], off
	v_lshl_add_u64 v[28:29], v[10:11], 0, s[68:69]
	s_mov_b32 m0, s34
	v_readfirstlane_b32 s35, v0
	global_load_lds_dwordx4 v[28:29], off
	v_lshl_add_u64 v[28:29], v[26:27], 0, s[38:39]
	s_mov_b32 m0, s35
	v_or_b32_e32 v0, v36, v37
	global_load_lds_dwordx4 v[28:29], off
	v_or_b32_e32 v28, v36, v30
	v_or_b32_e32 v29, v31, v37
	v_or_b32_e32 v30, v31, v30
	ds_read_b128 v[32:35], v0
	ds_read_b128 v[42:45], v0 offset:2048
	ds_read_b128 v[50:53], v0 offset:4096
	ds_read_b128 v[62:65], v0 offset:6144
	ds_read_b128 v[66:69], v28 offset:16384
	ds_read_b128 v[70:73], v28 offset:18432
	ds_read_b128 v[74:77], v28 offset:20480
	ds_read_b128 v[78:81], v28 offset:22528
	ds_read_b128 v[82:85], v29
	ds_read_b128 v[86:89], v29 offset:2048
	ds_read_b128 v[90:93], v29 offset:4096
	ds_read_b128 v[94:97], v29 offset:6144
	ds_read_b128 v[100:103], v30 offset:16384
	ds_read_b128 v[104:107], v30 offset:18432
	ds_read_b128 v[108:111], v30 offset:20480
	ds_read_b128 v[112:115], v30 offset:22528
	v_and_b32_e32 v98, 15, v99
	s_setprio 1
	s_waitcnt lgkmcnt(8)
	v_mfma_f32_16x16x32_bf16 v[116:119], v[32:35], v[66:69], 0
	v_mfma_f32_16x16x32_bf16 v[120:123], v[32:35], v[70:73], 0
	v_mfma_f32_16x16x32_bf16 v[124:127], v[32:35], v[74:77], 0
	v_mfma_f32_16x16x32_bf16 v[32:35], v[32:35], v[78:81], 0
	v_mfma_f32_16x16x32_bf16 v[128:131], v[42:45], v[66:69], 0
	v_mfma_f32_16x16x32_bf16 v[132:135], v[42:45], v[70:73], 0
	v_mfma_f32_16x16x32_bf16 v[136:139], v[42:45], v[74:77], 0
	v_mfma_f32_16x16x32_bf16 v[42:45], v[42:45], v[78:81], 0
	v_mfma_f32_16x16x32_bf16 v[140:143], v[50:53], v[66:69], 0
	v_mfma_f32_16x16x32_bf16 v[144:147], v[50:53], v[70:73], 0
	v_mfma_f32_16x16x32_bf16 v[148:151], v[50:53], v[74:77], 0
	v_mfma_f32_16x16x32_bf16 v[50:53], v[50:53], v[78:81], 0
	v_mfma_f32_16x16x32_bf16 v[66:69], v[62:65], v[66:69], 0
	v_mfma_f32_16x16x32_bf16 v[70:73], v[62:65], v[70:73], 0
	v_mfma_f32_16x16x32_bf16 v[74:77], v[62:65], v[74:77], 0
	v_mfma_f32_16x16x32_bf16 v[62:65], v[62:65], v[78:81], 0
	s_waitcnt lgkmcnt(0)
	v_mfma_f32_16x16x32_bf16 v[78:81], v[82:85], v[100:103], v[116:119]
	v_mfma_f32_16x16x32_bf16 v[116:119], v[82:85], v[104:107], v[120:123]
	v_mfma_f32_16x16x32_bf16 v[120:123], v[82:85], v[108:111], v[124:127]
	v_mfma_f32_16x16x32_bf16 v[32:35], v[82:85], v[112:115], v[32:35]
	v_mfma_f32_16x16x32_bf16 v[82:85], v[86:89], v[100:103], v[128:131]
	v_mfma_f32_16x16x32_bf16 v[124:127], v[86:89], v[104:107], v[132:135]
	v_mfma_f32_16x16x32_bf16 v[128:131], v[86:89], v[108:111], v[136:139]
	v_mfma_f32_16x16x32_bf16 v[42:45], v[86:89], v[112:115], v[42:45]
	v_mfma_f32_16x16x32_bf16 v[86:89], v[90:93], v[100:103], v[140:143]
	v_mfma_f32_16x16x32_bf16 v[132:135], v[90:93], v[104:107], v[144:147]
	v_mfma_f32_16x16x32_bf16 v[136:139], v[90:93], v[108:111], v[148:151]
	v_mfma_f32_16x16x32_bf16 v[50:53], v[90:93], v[112:115], v[50:53]
	v_mfma_f32_16x16x32_bf16 v[66:69], v[94:97], v[100:103], v[66:69]
	v_mfma_f32_16x16x32_bf16 v[70:73], v[94:97], v[104:107], v[70:73]
	v_mfma_f32_16x16x32_bf16 v[74:77], v[94:97], v[108:111], v[74:77]
	v_mfma_f32_16x16x32_bf16 v[62:65], v[94:97], v[112:115], v[62:65]
	s_setprio 0
	s_mov_b64 s[36:37], 0x100
	s_mov_b32 m0, s5
	v_lshl_add_u64 v[36:37], v[10:11], 0, s[36:37]
	s_waitcnt vmcnt(0)
	s_barrier
	global_load_lds_dwordx4 v[36:37], off
	v_lshl_add_u64 v[36:37], v[12:13], 0, s[36:37]
	s_mov_b32 m0, s10
	s_mov_b64 s[70:71], 0x8100
	global_load_lds_dwordx4 v[36:37], off
	v_lshl_add_u64 v[36:37], v[10:11], 0, s[70:71]
	s_mov_b32 m0, s11
	s_mov_b64 s[92:93], 0x10100
	global_load_lds_dwordx4 v[36:37], off
	v_lshl_add_u64 v[36:37], v[22:23], 0, s[36:37]
	s_mov_b32 m0, s21
	s_mov_b64 s[0:1], 0x18100
	global_load_lds_dwordx4 v[36:37], off
	v_lshl_add_u64 v[36:37], v[10:11], 0, s[92:93]
	s_mov_b32 m0, s22
	s_nop 0
	global_load_lds_dwordx4 v[36:37], off
	v_lshl_add_u64 v[36:37], v[24:25], 0, s[36:37]
	s_mov_b32 m0, s23
	s_nop 0
	global_load_lds_dwordx4 v[36:37], off
	v_lshl_add_u64 v[36:37], v[10:11], 0, s[0:1]
	s_mov_b32 m0, s24
	s_nop 0
	global_load_lds_dwordx4 v[36:37], off
	v_lshl_add_u64 v[36:37], v[26:27], 0, s[36:37]
	s_mov_b32 m0, s25
	s_nop 0
	global_load_lds_dwordx4 v[36:37], off
	ds_read_b128 v[90:93], v0 offset:32768
	ds_read_b128 v[94:97], v0 offset:34816
	ds_read_b128 v[100:103], v0 offset:36864
	ds_read_b128 v[104:107], v0 offset:38912
	ds_read_b128 v[108:111], v28 offset:49152
	ds_read_b128 v[112:115], v28 offset:51200
	ds_read_b128 v[140:143], v28 offset:53248
	ds_read_b128 v[144:147], v28 offset:55296
	ds_read_b128 v[148:151], v29 offset:32768
	ds_read_b128 v[152:155], v29 offset:34816
	ds_read_b128 v[180:183], v29 offset:36864
	ds_read_b128 v[184:187], v29 offset:38912
	ds_read_b128 v[188:191], v30 offset:49152
	ds_read_b128 v[192:195], v30 offset:51200
	ds_read_b128 v[196:199], v30 offset:53248
	ds_read_b128 v[200:203], v30 offset:55296
	s_setprio 1
	s_waitcnt lgkmcnt(8)
; #define MFMA16(a, b, c) __builtin_amdgcn_mfma_f32_16x16x32_bf16((a), (b), (c), 0, 0, 0)
; DI void gemm_tile(const bf16_t* __restrict__ A, int lda, const bf16_t* __restrict__ Bt, int ldb, int bvalid, int K, f32x4 (&acc)[4][4], char* lds, bool preloaded = false) {
;     ...
;   auto compute = [&](int st) {
;     const char* base = lds + st * 32768;
;     bf16x8 af[2][4], bfr[2][4];
; #pragma unroll
;     for (int s = 0; s < 2; ++s) {
;       const int ch = ((4 * s + fq) ^ fx) << 4;
; #pragma unroll
;       for (int mi = 0; mi < 4; ++mi) af[s][mi] = *(const bf16x8*)(base + (wm * 64 + mi * 16 + fr) * 128 + ch);
; #pragma unroll
;       for (int ni = 0; ni < 4; ++ni) bfr[s][ni] = *(const bf16x8*)(base + 16384 + (wn * 64 + ni * 16 + fr) * 128 + ch);
;     }
;     __builtin_amdgcn_s_setprio(1);
; #pragma unroll
;     for (int s = 0; s < 2; ++s)
; #pragma unroll
;       for (int mi = 0; mi < 4; ++mi)
; #pragma unroll
;         for (int ni = 0; ni < 4; ++ni) acc[mi][ni] = MFMA16(af[s][mi], bfr[s][ni], acc[mi][ni]);
;     __builtin_amdgcn_s_setprio(0);
;   };
;   const int nk = K >> 6;
;   if (!preloaded) { GLDS(0, 0) }
;   __syncthreads();
;   for (int kt = 0; kt < nk; ++kt) {
;     if (kt + 1 < nk) { GLDS((kt + 1) & 1, (kt + 1) << 6) }
;     compute(kt & 1);
;     __syncthreads();
;   }
	v_mfma_f32_16x16x32_bf16 v[78:81], v[90:93], v[108:111], v[78:81]
	v_mfma_f32_16x16x32_bf16 v[116:119], v[90:93], v[112:115], v[116:119]
	v_mfma_f32_16x16x32_bf16 v[120:123], v[90:93], v[140:143], v[120:123]
	v_mfma_f32_16x16x32_bf16 v[32:35], v[90:93], v[144:147], v[32:35]
	v_mfma_f32_16x16x32_bf16 v[82:85], v[94:97], v[108:111], v[82:85]
	v_mfma_f32_16x16x32_bf16 v[90:93], v[94:97], v[112:115], v[124:127]
	v_mfma_f32_16x16x32_bf16 v[124:127], v[94:97], v[140:143], v[128:131]
	v_mfma_f32_16x16x32_bf16 v[42:45], v[94:97], v[144:147], v[42:45]
	v_mfma_f32_16x16x32_bf16 v[86:89], v[100:103], v[108:111], v[86:89]
	v_mfma_f32_16x16x32_bf16 v[94:97], v[100:103], v[112:115], v[132:135]
	v_mfma_f32_16x16x32_bf16 v[128:131], v[100:103], v[140:143], v[136:139]
	v_mfma_f32_16x16x32_bf16 v[50:53], v[100:103], v[144:147], v[50:53]
	v_mfma_f32_16x16x32_bf16 v[66:69], v[104:107], v[108:111], v[66:69]
	v_mfma_f32_16x16x32_bf16 v[70:73], v[104:107], v[112:115], v[70:73]
	v_mfma_f32_16x16x32_bf16 v[74:77], v[104:107], v[140:143], v[74:77]
	v_mfma_f32_16x16x32_bf16 v[62:65], v[104:107], v[144:147], v[62:65]
	s_waitcnt lgkmcnt(0)
	v_mfma_f32_16x16x32_bf16 v[78:81], v[148:151], v[188:191], v[78:81]
	v_mfma_f32_16x16x32_bf16 v[100:103], v[148:151], v[192:195], v[116:119]
	v_mfma_f32_16x16x32_bf16 v[104:107], v[148:151], v[196:199], v[120:123]
	v_mfma_f32_16x16x32_bf16 v[32:35], v[148:151], v[200:203], v[32:35]
	v_mfma_f32_16x16x32_bf16 v[82:85], v[152:155], v[188:191], v[82:85]
	v_mfma_f32_16x16x32_bf16 v[90:93], v[152:155], v[192:195], v[90:93]
	v_mfma_f32_16x16x32_bf16 v[108:111], v[152:155], v[196:199], v[124:127]
	v_mfma_f32_16x16x32_bf16 v[42:45], v[152:155], v[200:203], v[42:45]
	v_mfma_f32_16x16x32_bf16 v[86:89], v[180:183], v[188:191], v[86:89]
	v_mfma_f32_16x16x32_bf16 v[94:97], v[180:183], v[192:195], v[94:97]
	v_mfma_f32_16x16x32_bf16 v[112:115], v[180:183], v[196:199], v[128:131]
	v_mfma_f32_16x16x32_bf16 v[50:53], v[180:183], v[200:203], v[50:53]
	v_mfma_f32_16x16x32_bf16 v[66:69], v[184:187], v[188:191], v[66:69]
	v_mfma_f32_16x16x32_bf16 v[70:73], v[184:187], v[192:195], v[70:73]
	v_mfma_f32_16x16x32_bf16 v[74:77], v[184:187], v[196:199], v[74:77]
	v_mfma_f32_16x16x32_bf16 v[62:65], v[184:187], v[200:203], v[62:65]
	s_setprio 0
	s_mov_b64 s[0:1], 0x180
	s_mov_b32 m0, s29
	v_lshl_add_u64 v[36:37], v[10:11], 0, s[0:1]
	s_waitcnt vmcnt(0)
	s_barrier
	global_load_lds_dwordx4 v[36:37], off
	v_lshl_add_u64 v[36:37], v[12:13], 0, s[0:1]
	s_mov_b32 m0, s26
	s_mov_b64 s[2:3], 0x8180
	global_load_lds_dwordx4 v[36:37], off
	v_lshl_add_u64 v[36:37], v[10:11], 0, s[2:3]
	s_mov_b32 m0, s27
	s_mov_b64 s[2:3], 0x10180
	global_load_lds_dwordx4 v[36:37], off
	v_lshl_add_u64 v[36:37], v[22:23], 0, s[0:1]
	s_mov_b32 m0, s28
	s_nop 0
	global_load_lds_dwordx4 v[36:37], off
	v_lshl_add_u64 v[36:37], v[10:11], 0, s[2:3]
	s_mov_b32 m0, s30
	s_mov_b64 s[2:3], 0x18180
	global_load_lds_dwordx4 v[36:37], off
	v_lshl_add_u64 v[36:37], v[24:25], 0, s[0:1]
	s_mov_b32 m0, s31
	s_nop 0
	global_load_lds_dwordx4 v[36:37], off
	v_lshl_add_u64 v[36:37], v[10:11], 0, s[2:3]
	s_mov_b32 m0, s34
	s_nop 0
	global_load_lds_dwordx4 v[36:37], off
	v_lshl_add_u64 v[36:37], v[26:27], 0, s[0:1]
	s_mov_b32 m0, s35
	s_nop 0
	global_load_lds_dwordx4 v[36:37], off
	ds_read_b128 v[116:119], v0
	ds_read_b128 v[120:123], v0 offset:2048
	ds_read_b128 v[124:127], v0 offset:4096
	ds_read_b128 v[128:131], v0 offset:6144
	ds_read_b128 v[132:135], v28 offset:16384
	ds_read_b128 v[136:139], v28 offset:18432
	ds_read_b128 v[140:143], v28 offset:20480
	ds_read_b128 v[144:147], v28 offset:22528
	ds_read_b128 v[148:151], v29
	ds_read_b128 v[152:155], v29 offset:2048
	ds_read_b128 v[180:183], v29 offset:4096
	ds_read_b128 v[184:187], v29 offset:6144
	ds_read_b128 v[188:191], v30 offset:16384
	ds_read_b128 v[192:195], v30 offset:18432
	ds_read_b128 v[196:199], v30 offset:20480
	ds_read_b128 v[200:203], v30 offset:22528
	s_setprio 1
	s_waitcnt lgkmcnt(8)
	v_mfma_f32_16x16x32_bf16 v[78:81], v[116:119], v[132:135], v[78:81]
	v_mfma_f32_16x16x32_bf16 v[100:103], v[116:119], v[136:139], v[100:103]
	v_mfma_f32_16x16x32_bf16 v[104:107], v[116:119], v[140:143], v[104:107]
	v_mfma_f32_16x16x32_bf16 v[32:35], v[116:119], v[144:147], v[32:35]
	v_mfma_f32_16x16x32_bf16 v[82:85], v[120:123], v[132:135], v[82:85]
	v_mfma_f32_16x16x32_bf16 v[90:93], v[120:123], v[136:139], v[90:93]
	v_mfma_f32_16x16x32_bf16 v[108:111], v[120:123], v[140:143], v[108:111]
	v_mfma_f32_16x16x32_bf16 v[42:45], v[120:123], v[144:147], v[42:45]
	v_mfma_f32_16x16x32_bf16 v[86:89], v[124:127], v[132:135], v[86:89]
	v_mfma_f32_16x16x32_bf16 v[94:97], v[124:127], v[136:139], v[94:97]
	v_mfma_f32_16x16x32_bf16 v[112:115], v[124:127], v[140:143], v[112:115]
	v_mfma_f32_16x16x32_bf16 v[50:53], v[124:127], v[144:147], v[50:53]
	v_mfma_f32_16x16x32_bf16 v[66:69], v[128:131], v[132:135], v[66:69]
	v_mfma_f32_16x16x32_bf16 v[70:73], v[128:131], v[136:139], v[70:73]
	v_mfma_f32_16x16x32_bf16 v[74:77], v[128:131], v[140:143], v[74:77]
	v_mfma_f32_16x16x32_bf16 v[62:65], v[128:131], v[144:147], v[62:65]
	s_waitcnt lgkmcnt(0)
	v_mfma_f32_16x16x32_bf16 v[78:81], v[148:151], v[188:191], v[78:81]
	v_mfma_f32_16x16x32_bf16 v[100:103], v[148:151], v[192:195], v[100:103]
	v_mfma_f32_16x16x32_bf16 v[104:107], v[148:151], v[196:199], v[104:107]
	v_mfma_f32_16x16x32_bf16 v[32:35], v[148:151], v[200:203], v[32:35]
	v_mfma_f32_16x16x32_bf16 v[82:85], v[152:155], v[188:191], v[82:85]
	v_mfma_f32_16x16x32_bf16 v[90:93], v[152:155], v[192:195], v[90:93]
	v_mfma_f32_16x16x32_bf16 v[108:111], v[152:155], v[196:199], v[108:111]
	v_mfma_f32_16x16x32_bf16 v[42:45], v[152:155], v[200:203], v[42:45]
	v_mfma_f32_16x16x32_bf16 v[86:89], v[180:183], v[188:191], v[86:89]
	v_mfma_f32_16x16x32_bf16 v[94:97], v[180:183], v[192:195], v[94:97]
	v_mfma_f32_16x16x32_bf16 v[112:115], v[180:183], v[196:199], v[112:115]
	v_mfma_f32_16x16x32_bf16 v[50:53], v[180:183], v[200:203], v[50:53]
	v_mfma_f32_16x16x32_bf16 v[66:69], v[184:187], v[188:191], v[66:69]
	v_mfma_f32_16x16x32_bf16 v[70:73], v[184:187], v[192:195], v[70:73]
	v_mfma_f32_16x16x32_bf16 v[74:77], v[184:187], v[196:199], v[74:77]
	v_mfma_f32_16x16x32_bf16 v[62:65], v[184:187], v[200:203], v[62:65]
	s_setprio 0
	s_mov_b64 s[36:37], 0x200
	s_mov_b32 m0, s5
	v_lshl_add_u64 v[36:37], v[10:11], 0, s[36:37]
	s_waitcnt vmcnt(0)
	s_barrier
; #define MFMA16(a, b, c) __builtin_amdgcn_mfma_f32_16x16x32_bf16((a), (b), (c), 0, 0, 0)
; DI void gemm_tile(const bf16_t* __restrict__ A, int lda, const bf16_t* __restrict__ Bt, int ldb, int bvalid, int K, f32x4 (&acc)[4][4], char* lds, bool preloaded = false) {
;     ...
;   auto compute = [&](int st) {
;     const char* base = lds + st * 32768;
;     bf16x8 af[2][4], bfr[2][4];
; #pragma unroll
;     for (int s = 0; s < 2; ++s) {
;       const int ch = ((4 * s + fq) ^ fx) << 4;
; #pragma unroll
;       for (int mi = 0; mi < 4; ++mi) af[s][mi] = *(const bf16x8*)(base + (wm * 64 + mi * 16 + fr) * 128 + ch);
; #pragma unroll
;       for (int ni = 0; ni < 4; ++ni) bfr[s][ni] = *(const bf16x8*)(base + 16384 + (wn * 64 + ni * 16 + fr) * 128 + ch);
;     }
;     __builtin_amdgcn_s_setprio(1);
; #pragma unroll
;     for (int s = 0; s < 2; ++s)
; #pragma unroll
;       for (int mi = 0; mi < 4; ++mi)
; #pragma unroll
;         for (int ni = 0; ni < 4; ++ni) acc[mi][ni] = MFMA16(af[s][mi], bfr[s][ni], acc[mi][ni]);
;     __builtin_amdgcn_s_setprio(0);
;   };
;   const int nk = K >> 6;
;   if (!preloaded) { GLDS(0, 0) }
;   __syncthreads();
;   for (int kt = 0; kt < nk; ++kt) {
;     if (kt + 1 < nk) { GLDS((kt + 1) & 1, (kt + 1) << 6) }
;     compute(kt & 1);
;     __syncthreads();
;   }
	global_load_lds_dwordx4 v[36:37], off
	v_lshl_add_u64 v[36:37], v[12:13], 0, s[36:37]
	s_mov_b32 m0, s10
	s_mov_b64 s[2:3], 0x8200
	global_load_lds_dwordx4 v[36:37], off
	v_lshl_add_u64 v[36:37], v[10:11], 0, s[2:3]
	s_mov_b32 m0, s11
	s_mov_b64 s[2:3], 0x10200
	global_load_lds_dwordx4 v[36:37], off
	v_lshl_add_u64 v[36:37], v[22:23], 0, s[36:37]
	s_mov_b32 m0, s21
	s_nop 0
	global_load_lds_dwordx4 v[36:37], off
	v_lshl_add_u64 v[36:37], v[10:11], 0, s[2:3]
	s_mov_b32 m0, s22
	s_mov_b64 s[2:3], 0x18200
	global_load_lds_dwordx4 v[36:37], off
	v_lshl_add_u64 v[36:37], v[24:25], 0, s[36:37]
	s_mov_b32 m0, s23
	s_nop 0
	global_load_lds_dwordx4 v[36:37], off
	v_lshl_add_u64 v[36:37], v[10:11], 0, s[2:3]
	s_mov_b32 m0, s24
	s_nop 0
	global_load_lds_dwordx4 v[36:37], off
	v_lshl_add_u64 v[36:37], v[26:27], 0, s[36:37]
	s_mov_b32 m0, s25
	s_nop 0
	global_load_lds_dwordx4 v[36:37], off
	ds_read_b128 v[116:119], v0 offset:32768
	ds_read_b128 v[120:123], v0 offset:34816
	ds_read_b128 v[124:127], v0 offset:36864
	ds_read_b128 v[128:131], v0 offset:38912
	ds_read_b128 v[132:135], v28 offset:49152
	ds_read_b128 v[136:139], v28 offset:51200
	ds_read_b128 v[140:143], v28 offset:53248
	ds_read_b128 v[144:147], v28 offset:55296
	ds_read_b128 v[148:151], v29 offset:32768
	ds_read_b128 v[152:155], v29 offset:34816
	ds_read_b128 v[180:183], v29 offset:36864
	ds_read_b128 v[184:187], v29 offset:38912
	ds_read_b128 v[188:191], v30 offset:49152
	ds_read_b128 v[192:195], v30 offset:51200
	ds_read_b128 v[196:199], v30 offset:53248
	ds_read_b128 v[200:203], v30 offset:55296
	s_setprio 1
	s_waitcnt lgkmcnt(8)
	v_mfma_f32_16x16x32_bf16 v[78:81], v[116:119], v[132:135], v[78:81]
	v_mfma_f32_16x16x32_bf16 v[100:103], v[116:119], v[136:139], v[100:103]
	v_mfma_f32_16x16x32_bf16 v[104:107], v[116:119], v[140:143], v[104:107]
	v_mfma_f32_16x16x32_bf16 v[32:35], v[116:119], v[144:147], v[32:35]
	v_mfma_f32_16x16x32_bf16 v[82:85], v[120:123], v[132:135], v[82:85]
	v_mfma_f32_16x16x32_bf16 v[90:93], v[120:123], v[136:139], v[90:93]
	v_mfma_f32_16x16x32_bf16 v[108:111], v[120:123], v[140:143], v[108:111]
	v_mfma_f32_16x16x32_bf16 v[42:45], v[120:123], v[144:147], v[42:45]
	v_mfma_f32_16x16x32_bf16 v[86:89], v[124:127], v[132:135], v[86:89]
	v_mfma_f32_16x16x32_bf16 v[94:97], v[124:127], v[136:139], v[94:97]
	v_mfma_f32_16x16x32_bf16 v[112:115], v[124:127], v[140:143], v[112:115]
	v_mfma_f32_16x16x32_bf16 v[50:53], v[124:127], v[144:147], v[50:53]
	v_mfma_f32_16x16x32_bf16 v[66:69], v[128:131], v[132:135], v[66:69]
	v_mfma_f32_16x16x32_bf16 v[70:73], v[128:131], v[136:139], v[70:73]
	v_mfma_f32_16x16x32_bf16 v[74:77], v[128:131], v[140:143], v[74:77]
	v_mfma_f32_16x16x32_bf16 v[62:65], v[128:131], v[144:147], v[62:65]
	s_waitcnt lgkmcnt(0)
	v_mfma_f32_16x16x32_bf16 v[78:81], v[148:151], v[188:191], v[78:81]
	v_mfma_f32_16x16x32_bf16 v[100:103], v[148:151], v[192:195], v[100:103]
	v_mfma_f32_16x16x32_bf16 v[104:107], v[148:151], v[196:199], v[104:107]
	v_mfma_f32_16x16x32_bf16 v[32:35], v[148:151], v[200:203], v[32:35]
	v_mfma_f32_16x16x32_bf16 v[82:85], v[152:155], v[188:191], v[82:85]
	v_mfma_f32_16x16x32_bf16 v[90:93], v[152:155], v[192:195], v[90:93]
	v_mfma_f32_16x16x32_bf16 v[108:111], v[152:155], v[196:199], v[108:111]
	v_mfma_f32_16x16x32_bf16 v[42:45], v[152:155], v[200:203], v[42:45]
	v_mfma_f32_16x16x32_bf16 v[86:89], v[180:183], v[188:191], v[86:89]
	v_mfma_f32_16x16x32_bf16 v[94:97], v[180:183], v[192:195], v[94:97]
	v_mfma_f32_16x16x32_bf16 v[112:115], v[180:183], v[196:199], v[112:115]
	v_mfma_f32_16x16x32_bf16 v[50:53], v[180:183], v[200:203], v[50:53]
	v_mfma_f32_16x16x32_bf16 v[66:69], v[184:187], v[188:191], v[66:69]
	v_mfma_f32_16x16x32_bf16 v[70:73], v[184:187], v[192:195], v[70:73]
	v_mfma_f32_16x16x32_bf16 v[74:77], v[184:187], v[196:199], v[74:77]
	v_mfma_f32_16x16x32_bf16 v[62:65], v[184:187], v[200:203], v[62:65]
	s_setprio 0
	s_mov_b64 s[2:3], 0x280
	s_mov_b32 m0, s29
	v_lshl_add_u64 v[36:37], v[10:11], 0, s[2:3]
	s_waitcnt vmcnt(0)
	s_barrier
	global_load_lds_dwordx4 v[36:37], off
	v_lshl_add_u64 v[36:37], v[12:13], 0, s[2:3]
	s_mov_b32 m0, s26
	s_mov_b64 s[14:15], 0x8280
	global_load_lds_dwordx4 v[36:37], off
	v_lshl_add_u64 v[36:37], v[10:11], 0, s[14:15]
	s_mov_b32 m0, s27
	s_mov_b64 s[14:15], 0x10280
	global_load_lds_dwordx4 v[36:37], off
	v_lshl_add_u64 v[36:37], v[22:23], 0, s[2:3]
	s_mov_b32 m0, s28
	s_nop 0
	global_load_lds_dwordx4 v[36:37], off
	v_lshl_add_u64 v[36:37], v[10:11], 0, s[14:15]
	s_mov_b32 m0, s30
	s_mov_b64 s[14:15], 0x18280
	global_load_lds_dwordx4 v[36:37], off
	v_lshl_add_u64 v[36:37], v[24:25], 0, s[2:3]
	s_mov_b32 m0, s31
	s_nop 0
	global_load_lds_dwordx4 v[36:37], off
	v_lshl_add_u64 v[36:37], v[10:11], 0, s[14:15]
	s_mov_b32 m0, s34
	s_nop 0
	global_load_lds_dwordx4 v[36:37], off
	v_lshl_add_u64 v[36:37], v[26:27], 0, s[2:3]
	s_mov_b32 m0, s35
	s_nop 0
	global_load_lds_dwordx4 v[36:37], off
	ds_read_b128 v[116:119], v0
	ds_read_b128 v[120:123], v0 offset:2048
	ds_read_b128 v[124:127], v0 offset:4096
	ds_read_b128 v[128:131], v0 offset:6144
	ds_read_b128 v[132:135], v28 offset:16384
	ds_read_b128 v[136:139], v28 offset:18432
	ds_read_b128 v[140:143], v28 offset:20480
	ds_read_b128 v[144:147], v28 offset:22528
	ds_read_b128 v[148:151], v29
	ds_read_b128 v[152:155], v29 offset:2048
	ds_read_b128 v[180:183], v29 offset:4096
	ds_read_b128 v[184:187], v29 offset:6144
	ds_read_b128 v[188:191], v30 offset:16384
	ds_read_b128 v[192:195], v30 offset:18432
	ds_read_b128 v[196:199], v30 offset:20480
	ds_read_b128 v[200:203], v30 offset:22528
	s_setprio 1
	s_waitcnt lgkmcnt(8)
; #define MFMA16(a, b, c) __builtin_amdgcn_mfma_f32_16x16x32_bf16((a), (b), (c), 0, 0, 0)
; DI void gemm_tile(const bf16_t* __restrict__ A, int lda, const bf16_t* __restrict__ Bt, int ldb, int bvalid, int K, f32x4 (&acc)[4][4], char* lds, bool preloaded = false) {
;     ...
;   auto compute = [&](int st) {
;     const char* base = lds + st * 32768;
;     bf16x8 af[2][4], bfr[2][4];
; #pragma unroll
;     for (int s = 0; s < 2; ++s) {
;       const int ch = ((4 * s + fq) ^ fx) << 4;
; #pragma unroll
;       for (int mi = 0; mi < 4; ++mi) af[s][mi] = *(const bf16x8*)(base + (wm * 64 + mi * 16 + fr) * 128 + ch);
; #pragma unroll
;       for (int ni = 0; ni < 4; ++ni) bfr[s][ni] = *(const bf16x8*)(base + 16384 + (wn * 64 + ni * 16 + fr) * 128 + ch);
;     }
;     __builtin_amdgcn_s_setprio(1);
; #pragma unroll
;     for (int s = 0; s < 2; ++s)
; #pragma unroll
;       for (int mi = 0; mi < 4; ++mi)
; #pragma unroll
;         for (int ni = 0; ni < 4; ++ni) acc[mi][ni] = MFMA16(af[s][mi], bfr[s][ni], acc[mi][ni]);
;     __builtin_amdgcn_s_setprio(0);
;   };
;   const int nk = K >> 6;
;   if (!preloaded) { GLDS(0, 0) }
;   __syncthreads();
;   for (int kt = 0; kt < nk; ++kt) {
;     if (kt + 1 < nk) { GLDS((kt + 1) & 1, (kt + 1) << 6) }
;     compute(kt & 1);
;     __syncthreads();
;   }
	v_mfma_f32_16x16x32_bf16 v[78:81], v[116:119], v[132:135], v[78:81]
	v_mfma_f32_16x16x32_bf16 v[100:103], v[116:119], v[136:139], v[100:103]
	v_mfma_f32_16x16x32_bf16 v[104:107], v[116:119], v[140:143], v[104:107]
	v_mfma_f32_16x16x32_bf16 v[32:35], v[116:119], v[144:147], v[32:35]
	v_mfma_f32_16x16x32_bf16 v[82:85], v[120:123], v[132:135], v[82:85]
	v_mfma_f32_16x16x32_bf16 v[90:93], v[120:123], v[136:139], v[90:93]
	v_mfma_f32_16x16x32_bf16 v[108:111], v[120:123], v[140:143], v[108:111]
	v_mfma_f32_16x16x32_bf16 v[42:45], v[120:123], v[144:147], v[42:45]
	v_mfma_f32_16x16x32_bf16 v[86:89], v[124:127], v[132:135], v[86:89]
	v_mfma_f32_16x16x32_bf16 v[94:97], v[124:127], v[136:139], v[94:97]
	v_mfma_f32_16x16x32_bf16 v[112:115], v[124:127], v[140:143], v[112:115]
	v_mfma_f32_16x16x32_bf16 v[50:53], v[124:127], v[144:147], v[50:53]
	v_mfma_f32_16x16x32_bf16 v[66:69], v[128:131], v[132:135], v[66:69]
	v_mfma_f32_16x16x32_bf16 v[70:73], v[128:131], v[136:139], v[70:73]
	v_mfma_f32_16x16x32_bf16 v[74:77], v[128:131], v[140:143], v[74:77]
	v_mfma_f32_16x16x32_bf16 v[62:65], v[128:131], v[144:147], v[62:65]
	s_waitcnt lgkmcnt(0)
	v_mfma_f32_16x16x32_bf16 v[78:81], v[148:151], v[188:191], v[78:81]
	v_mfma_f32_16x16x32_bf16 v[100:103], v[148:151], v[192:195], v[100:103]
	v_mfma_f32_16x16x32_bf16 v[104:107], v[148:151], v[196:199], v[104:107]
	v_mfma_f32_16x16x32_bf16 v[32:35], v[148:151], v[200:203], v[32:35]
	v_mfma_f32_16x16x32_bf16 v[82:85], v[152:155], v[188:191], v[82:85]
	v_mfma_f32_16x16x32_bf16 v[90:93], v[152:155], v[192:195], v[90:93]
	v_mfma_f32_16x16x32_bf16 v[108:111], v[152:155], v[196:199], v[108:111]
	v_mfma_f32_16x16x32_bf16 v[42:45], v[152:155], v[200:203], v[42:45]
	v_mfma_f32_16x16x32_bf16 v[86:89], v[180:183], v[188:191], v[86:89]
	v_mfma_f32_16x16x32_bf16 v[94:97], v[180:183], v[192:195], v[94:97]
	v_mfma_f32_16x16x32_bf16 v[112:115], v[180:183], v[196:199], v[112:115]
	v_mfma_f32_16x16x32_bf16 v[50:53], v[180:183], v[200:203], v[50:53]
	v_mfma_f32_16x16x32_bf16 v[66:69], v[184:187], v[188:191], v[66:69]
	v_mfma_f32_16x16x32_bf16 v[70:73], v[184:187], v[192:195], v[70:73]
	v_mfma_f32_16x16x32_bf16 v[74:77], v[184:187], v[196:199], v[74:77]
	v_mfma_f32_16x16x32_bf16 v[62:65], v[184:187], v[200:203], v[62:65]
	s_setprio 0
	s_mov_b64 s[14:15], 0x300
	s_mov_b32 m0, s5
	v_lshl_add_u64 v[36:37], v[10:11], 0, s[14:15]
	s_waitcnt vmcnt(0)
	s_barrier
	global_load_lds_dwordx4 v[36:37], off
	v_lshl_add_u64 v[36:37], v[12:13], 0, s[14:15]
	s_mov_b32 m0, s10
	s_mov_b64 s[64:65], 0x8300
	global_load_lds_dwordx4 v[36:37], off
	v_lshl_add_u64 v[36:37], v[10:11], 0, s[64:65]
	s_mov_b32 m0, s11
	s_mov_b64 s[10:11], 0x10300
	global_load_lds_dwordx4 v[36:37], off
	v_lshl_add_u64 v[36:37], v[22:23], 0, s[14:15]
	s_mov_b32 m0, s21
	s_nop 0
	global_load_lds_dwordx4 v[36:37], off
	v_lshl_add_u64 v[36:37], v[10:11], 0, s[10:11]
	s_mov_b32 m0, s22
	s_mov_b64 s[10:11], 0x18300
	global_load_lds_dwordx4 v[36:37], off
	v_lshl_add_u64 v[36:37], v[24:25], 0, s[14:15]
	s_mov_b32 m0, s23
	s_nop 0
	global_load_lds_dwordx4 v[36:37], off
	v_lshl_add_u64 v[36:37], v[10:11], 0, s[10:11]
	s_mov_b32 m0, s24
	s_nop 0
	global_load_lds_dwordx4 v[36:37], off
	v_lshl_add_u64 v[36:37], v[26:27], 0, s[14:15]
	s_mov_b32 m0, s25
	s_nop 0
	global_load_lds_dwordx4 v[36:37], off
	ds_read_b128 v[116:119], v0 offset:32768
	ds_read_b128 v[120:123], v0 offset:34816
	ds_read_b128 v[124:127], v0 offset:36864
	ds_read_b128 v[128:131], v0 offset:38912
	ds_read_b128 v[132:135], v28 offset:49152
	ds_read_b128 v[136:139], v28 offset:51200
	ds_read_b128 v[140:143], v28 offset:53248
	ds_read_b128 v[144:147], v28 offset:55296
	ds_read_b128 v[148:151], v29 offset:32768
	ds_read_b128 v[152:155], v29 offset:34816
	ds_read_b128 v[180:183], v29 offset:36864
	ds_read_b128 v[184:187], v29 offset:38912
	ds_read_b128 v[188:191], v30 offset:49152
	ds_read_b128 v[192:195], v30 offset:51200
	ds_read_b128 v[196:199], v30 offset:53248
	ds_read_b128 v[200:203], v30 offset:55296
	s_setprio 1
	s_waitcnt lgkmcnt(8)
	v_mfma_f32_16x16x32_bf16 v[78:81], v[116:119], v[132:135], v[78:81]
	v_mfma_f32_16x16x32_bf16 v[100:103], v[116:119], v[136:139], v[100:103]
	v_mfma_f32_16x16x32_bf16 v[104:107], v[116:119], v[140:143], v[104:107]
	v_mfma_f32_16x16x32_bf16 v[32:35], v[116:119], v[144:147], v[32:35]
	v_mfma_f32_16x16x32_bf16 v[82:85], v[120:123], v[132:135], v[82:85]
	v_mfma_f32_16x16x32_bf16 v[90:93], v[120:123], v[136:139], v[90:93]
	v_mfma_f32_16x16x32_bf16 v[108:111], v[120:123], v[140:143], v[108:111]
	v_mfma_f32_16x16x32_bf16 v[42:45], v[120:123], v[144:147], v[42:45]
	v_mfma_f32_16x16x32_bf16 v[86:89], v[124:127], v[132:135], v[86:89]
	v_mfma_f32_16x16x32_bf16 v[94:97], v[124:127], v[136:139], v[94:97]
	v_mfma_f32_16x16x32_bf16 v[112:115], v[124:127], v[140:143], v[112:115]
	v_mfma_f32_16x16x32_bf16 v[50:53], v[124:127], v[144:147], v[50:53]
	v_mfma_f32_16x16x32_bf16 v[66:69], v[128:131], v[132:135], v[66:69]
	v_mfma_f32_16x16x32_bf16 v[70:73], v[128:131], v[136:139], v[70:73]
	v_mfma_f32_16x16x32_bf16 v[74:77], v[128:131], v[140:143], v[74:77]
	v_mfma_f32_16x16x32_bf16 v[62:65], v[128:131], v[144:147], v[62:65]
	s_waitcnt lgkmcnt(0)
	v_mfma_f32_16x16x32_bf16 v[78:81], v[148:151], v[188:191], v[78:81]
	v_mfma_f32_16x16x32_bf16 v[100:103], v[148:151], v[192:195], v[100:103]
	v_mfma_f32_16x16x32_bf16 v[104:107], v[148:151], v[196:199], v[104:107]
	v_mfma_f32_16x16x32_bf16 v[32:35], v[148:151], v[200:203], v[32:35]
	v_mfma_f32_16x16x32_bf16 v[82:85], v[152:155], v[188:191], v[82:85]
	v_mfma_f32_16x16x32_bf16 v[90:93], v[152:155], v[192:195], v[90:93]
	v_mfma_f32_16x16x32_bf16 v[108:111], v[152:155], v[196:199], v[108:111]
	v_mfma_f32_16x16x32_bf16 v[42:45], v[152:155], v[200:203], v[42:45]
	v_mfma_f32_16x16x32_bf16 v[86:89], v[180:183], v[188:191], v[86:89]
	v_mfma_f32_16x16x32_bf16 v[94:97], v[180:183], v[192:195], v[94:97]
	v_mfma_f32_16x16x32_bf16 v[112:115], v[180:183], v[196:199], v[112:115]
	v_mfma_f32_16x16x32_bf16 v[50:53], v[180:183], v[200:203], v[50:53]
	v_mfma_f32_16x16x32_bf16 v[66:69], v[184:187], v[188:191], v[66:69]
	v_mfma_f32_16x16x32_bf16 v[70:73], v[184:187], v[192:195], v[70:73]
	v_mfma_f32_16x16x32_bf16 v[74:77], v[184:187], v[196:199], v[74:77]
	v_mfma_f32_16x16x32_bf16 v[62:65], v[184:187], v[200:203], v[62:65]
	s_setprio 0
	s_mov_b64 s[64:65], 0x380
	s_mov_b32 m0, s29
	v_lshl_add_u64 v[36:37], v[10:11], 0, s[64:65]
	s_waitcnt vmcnt(0)
	s_barrier
; #define MFMA16(a, b, c) __builtin_amdgcn_mfma_f32_16x16x32_bf16((a), (b), (c), 0, 0, 0)
; DI void gemm_tile(const bf16_t* __restrict__ A, int lda, const bf16_t* __restrict__ Bt, int ldb, int bvalid, int K, f32x4 (&acc)[4][4], char* lds, bool preloaded = false) {
;     ...
;   auto compute = [&](int st) {
;     const char* base = lds + st * 32768;
;     bf16x8 af[2][4], bfr[2][4];
; #pragma unroll
;     for (int s = 0; s < 2; ++s) {
;       const int ch = ((4 * s + fq) ^ fx) << 4;
; #pragma unroll
;       for (int mi = 0; mi < 4; ++mi) af[s][mi] = *(const bf16x8*)(base + (wm * 64 + mi * 16 + fr) * 128 + ch);
; #pragma unroll
;       for (int ni = 0; ni < 4; ++ni) bfr[s][ni] = *(const bf16x8*)(base + 16384 + (wn * 64 + ni * 16 + fr) * 128 + ch);
;     }
;     __builtin_amdgcn_s_setprio(1);
; #pragma unroll
;     for (int s = 0; s < 2; ++s)
; #pragma unroll
;       for (int mi = 0; mi < 4; ++mi)
; #pragma unroll
;         for (int ni = 0; ni < 4; ++ni) acc[mi][ni] = MFMA16(af[s][mi], bfr[s][ni], acc[mi][ni]);
;     __builtin_amdgcn_s_setprio(0);
;   };
;   const int nk = K >> 6;
;   if (!preloaded) { GLDS(0, 0) }
;   __syncthreads();
;   for (int kt = 0; kt < nk; ++kt) {
;     if (kt + 1 < nk) { GLDS((kt + 1) & 1, (kt + 1) << 6) }
;     compute(kt & 1);
;     __syncthreads();
;   }
	global_load_lds_dwordx4 v[36:37], off
	v_lshl_add_u64 v[12:13], v[12:13], 0, s[64:65]
	s_mov_b32 m0, s26
	s_mov_b64 s[10:11], 0x8380
	global_load_lds_dwordx4 v[12:13], off
	v_lshl_add_u64 v[12:13], v[10:11], 0, s[10:11]
	s_mov_b32 m0, s27
	s_mov_b64 s[10:11], 0x10380
	global_load_lds_dwordx4 v[12:13], off
	v_lshl_add_u64 v[12:13], v[22:23], 0, s[64:65]
	s_mov_b32 m0, s28
	s_nop 0
	global_load_lds_dwordx4 v[12:13], off
	v_lshl_add_u64 v[12:13], v[10:11], 0, s[10:11]
	s_mov_b32 m0, s30
	s_mov_b64 s[10:11], 0x18380
	global_load_lds_dwordx4 v[12:13], off
	v_lshl_add_u64 v[12:13], v[24:25], 0, s[64:65]
	s_mov_b32 m0, s31
	v_lshl_add_u64 v[10:11], v[10:11], 0, s[10:11]
	global_load_lds_dwordx4 v[12:13], off
	s_mov_b32 m0, s34
	s_nop 0
	global_load_lds_dwordx4 v[10:11], off
	v_lshl_add_u64 v[10:11], v[26:27], 0, s[64:65]
	s_mov_b32 m0, s35
	s_nop 0
	global_load_lds_dwordx4 v[10:11], off
	ds_read_b128 v[10:13], v0
	ds_read_b128 v[22:25], v0 offset:2048
	ds_read_b128 v[116:119], v0 offset:4096
	ds_read_b128 v[120:123], v0 offset:6144
	ds_read_b128 v[124:127], v28 offset:16384
	ds_read_b128 v[128:131], v28 offset:18432
	ds_read_b128 v[132:135], v28 offset:20480
	ds_read_b128 v[136:139], v28 offset:22528
	ds_read_b128 v[140:143], v29
	ds_read_b128 v[144:147], v29 offset:2048
	ds_read_b128 v[148:151], v29 offset:4096
	ds_read_b128 v[152:155], v29 offset:6144
	ds_read_b128 v[180:183], v30 offset:16384
	ds_read_b128 v[184:187], v30 offset:18432
	ds_read_b128 v[188:191], v30 offset:20480
	ds_read_b128 v[192:195], v30 offset:22528
	s_setprio 1
	s_waitcnt lgkmcnt(8)
	v_mfma_f32_16x16x32_bf16 v[78:81], v[10:13], v[124:127], v[78:81]
	v_mfma_f32_16x16x32_bf16 v[100:103], v[10:13], v[128:131], v[100:103]
	v_mfma_f32_16x16x32_bf16 v[104:107], v[10:13], v[132:135], v[104:107]
	v_mfma_f32_16x16x32_bf16 v[10:13], v[10:13], v[136:139], v[32:35]
	v_mfma_f32_16x16x32_bf16 v[32:35], v[22:25], v[124:127], v[82:85]
	v_mfma_f32_16x16x32_bf16 v[82:85], v[22:25], v[128:131], v[90:93]
	v_mfma_f32_16x16x32_bf16 v[90:93], v[22:25], v[132:135], v[108:111]
	v_mfma_f32_16x16x32_bf16 v[22:25], v[22:25], v[136:139], v[42:45]
	v_mfma_f32_16x16x32_bf16 v[42:45], v[116:119], v[124:127], v[86:89]
	v_mfma_f32_16x16x32_bf16 v[86:89], v[116:119], v[128:131], v[94:97]
	v_mfma_f32_16x16x32_bf16 v[94:97], v[116:119], v[132:135], v[112:115]
	v_mfma_f32_16x16x32_bf16 v[50:53], v[116:119], v[136:139], v[50:53]
	v_mfma_f32_16x16x32_bf16 v[66:69], v[120:123], v[124:127], v[66:69]
	v_mfma_f32_16x16x32_bf16 v[70:73], v[120:123], v[128:131], v[70:73]
	v_mfma_f32_16x16x32_bf16 v[74:77], v[120:123], v[132:135], v[74:77]
	v_mfma_f32_16x16x32_bf16 v[62:65], v[120:123], v[136:139], v[62:65]
	s_waitcnt lgkmcnt(0)
	v_mfma_f32_16x16x32_bf16 v[78:81], v[140:143], v[180:183], v[78:81]
	v_mfma_f32_16x16x32_bf16 v[100:103], v[140:143], v[184:187], v[100:103]
	v_mfma_f32_16x16x32_bf16 v[104:107], v[140:143], v[188:191], v[104:107]
	v_mfma_f32_16x16x32_bf16 v[10:13], v[140:143], v[192:195], v[10:13]
	v_mfma_f32_16x16x32_bf16 v[32:35], v[144:147], v[180:183], v[32:35]
	v_mfma_f32_16x16x32_bf16 v[82:85], v[144:147], v[184:187], v[82:85]
	v_mfma_f32_16x16x32_bf16 v[90:93], v[144:147], v[188:191], v[90:93]
	v_mfma_f32_16x16x32_bf16 v[22:25], v[144:147], v[192:195], v[22:25]
	v_mfma_f32_16x16x32_bf16 v[42:45], v[148:151], v[180:183], v[42:45]
	v_mfma_f32_16x16x32_bf16 v[86:89], v[148:151], v[184:187], v[86:89]
	v_mfma_f32_16x16x32_bf16 v[94:97], v[148:151], v[188:191], v[94:97]
	v_mfma_f32_16x16x32_bf16 v[50:53], v[148:151], v[192:195], v[50:53]
	v_mfma_f32_16x16x32_bf16 v[66:69], v[152:155], v[180:183], v[66:69]
	v_mfma_f32_16x16x32_bf16 v[70:73], v[152:155], v[184:187], v[70:73]
	v_mfma_f32_16x16x32_bf16 v[74:77], v[152:155], v[188:191], v[74:77]
	v_mfma_f32_16x16x32_bf16 v[62:65], v[152:155], v[192:195], v[62:65]
	s_setprio 0
	s_waitcnt vmcnt(0)
	s_barrier
	ds_read_b128 v[108:111], v0 offset:32768
	ds_read_b128 v[112:115], v0 offset:34816
	ds_read_b128 v[116:119], v0 offset:36864
	ds_read_b128 v[120:123], v0 offset:38912
	ds_read_b128 v[124:127], v28 offset:49152
	ds_read_b128 v[128:131], v28 offset:51200
	ds_read_b128 v[132:135], v28 offset:53248
	ds_read_b128 v[136:139], v28 offset:55296
	ds_read_b128 v[140:143], v29 offset:32768
	ds_read_b128 v[144:147], v29 offset:34816
	ds_read_b128 v[148:151], v29 offset:36864
	ds_read_b128 v[26:29], v29 offset:38912
	ds_read_b128 v[152:155], v30 offset:49152
	ds_read_b128 v[180:183], v30 offset:51200
	ds_read_b128 v[184:187], v30 offset:53248
	ds_read_b128 v[188:191], v30 offset:55296
	s_setprio 1
	s_waitcnt lgkmcnt(11)
	v_mfma_f32_16x16x32_bf16 v[78:81], v[108:111], v[124:127], v[78:81]
	s_waitcnt lgkmcnt(10)
	v_mfma_f32_16x16x32_bf16 v[100:103], v[108:111], v[128:131], v[100:103]
	s_waitcnt lgkmcnt(9)
	v_mfma_f32_16x16x32_bf16 v[104:107], v[108:111], v[132:135], v[104:107]
	s_waitcnt lgkmcnt(8)
	v_mfma_f32_16x16x32_bf16 v[108:111], v[108:111], v[136:139], v[10:13]
	v_mfma_f32_16x16x32_bf16 v[34:37], v[112:115], v[124:127], v[32:35]
	v_mfma_f32_16x16x32_bf16 v[82:85], v[112:115], v[128:131], v[82:85]
	v_mfma_f32_16x16x32_bf16 v[192:195], v[112:115], v[132:135], v[90:93]
	v_mfma_f32_16x16x32_bf16 v[112:115], v[112:115], v[136:139], v[22:25]
	v_mfma_f32_16x16x32_bf16 v[42:45], v[116:119], v[124:127], v[42:45]
	v_mfma_f32_16x16x32_bf16 v[196:199], v[116:119], v[128:131], v[86:89]
	v_mfma_f32_16x16x32_bf16 v[200:203], v[116:119], v[132:135], v[94:97]
	v_mfma_f32_16x16x32_bf16 v[50:53], v[116:119], v[136:139], v[50:53]
	v_mfma_f32_16x16x32_bf16 v[116:119], v[120:123], v[124:127], v[66:69]
	v_mfma_f32_16x16x32_bf16 v[124:127], v[120:123], v[128:131], v[70:73]
	v_mfma_f32_16x16x32_bf16 v[128:131], v[120:123], v[132:135], v[74:77]
	v_mfma_f32_16x16x32_bf16 v[120:123], v[120:123], v[136:139], v[62:65]
	s_waitcnt lgkmcnt(3)
	v_mfma_f32_16x16x32_bf16 v[10:13], v[140:143], v[152:155], v[78:81]
	s_waitcnt lgkmcnt(2)
	v_mfma_f32_16x16x32_bf16 v[22:25], v[140:143], v[180:183], v[100:103]
	s_waitcnt lgkmcnt(1)
	v_mfma_f32_16x16x32_bf16 v[30:33], v[140:143], v[184:187], v[104:107]
	s_waitcnt lgkmcnt(0)
	v_mfma_f32_16x16x32_bf16 v[94:97], v[140:143], v[188:191], v[108:111]
	v_mfma_f32_16x16x32_bf16 v[90:93], v[144:147], v[152:155], v[34:37]
	v_mfma_f32_16x16x32_bf16 v[62:65], v[144:147], v[180:183], v[82:85]
	v_mfma_f32_16x16x32_bf16 v[70:73], v[144:147], v[184:187], v[192:195]
	v_mfma_f32_16x16x32_bf16 v[86:89], v[144:147], v[188:191], v[112:115]
	v_mfma_f32_16x16x32_bf16 v[82:85], v[148:151], v[152:155], v[42:45]
	v_mfma_f32_16x16x32_bf16 v[78:81], v[148:151], v[180:183], v[196:199]
	v_mfma_f32_16x16x32_bf16 v[74:77], v[148:151], v[184:187], v[200:203]
	v_mfma_f32_16x16x32_bf16 v[66:69], v[148:151], v[188:191], v[50:53]
	v_mfma_f32_16x16x32_bf16 v[50:53], v[26:29], v[152:155], v[116:119]
	v_mfma_f32_16x16x32_bf16 v[42:45], v[26:29], v[180:183], v[124:127]
	v_mfma_f32_16x16x32_bf16 v[34:37], v[26:29], v[184:187], v[128:131]
	v_mfma_f32_16x16x32_bf16 v[26:29], v[26:29], v[188:191], v[120:123]
	s_setprio 0
	v_mov_b32_e32 v106, v158
	s_barrier
; DI int tidx() { int t = __builtin_amdgcn_workitem_id_x(); asm volatile("" : "+v"(t)); return t; }
; DI void gemm_prefetch0(const bf16_t* __restrict__ A, int lda, const bf16_t* __restrict__ Bt, int ldb, int bvalid, char* lds) {
;   const int tid = tidx();
;   const int lr = tid >> 3, lc = tid & 7;
;   const bf16_t* ap = A + (size_t)lr * lda + ((lc ^ ((lr >> 1) & 7)) << 3);
;   const bf16_t* bp = Bt + ((lc ^ ((lr >> 1) & 7)) << 3);
;   typedef __attribute__((address_space(1))) const unsigned gptr_t;
;   typedef __attribute__((address_space(3))) unsigned lptr_t;
;   const unsigned lbase = (unsigned)(size_t)lds + (unsigned)tid * 16u;
; #pragma unroll
;   for (int i = 0; i < 4; ++i) {
;     __builtin_amdgcn_global_load_lds((gptr_t*)(ap + (size_t)(32 * i) * lda), (lptr_t*)(lbase + i * 4096), 16, 0, 0);
;     __builtin_amdgcn_global_load_lds((gptr_t*)(bp + (size_t)((lr + 32 * i) & (bvalid - 1)) * ldb), (lptr_t*)(lbase + 16384 + i * 4096), 16, 0, 0);
;   }
; DI void phaseD_tile(const P& p, int layer, int mt, int nt, char* lds) {
;     ...
;   gemm_prefetch0((const bf16_t*)(p.ws + W_ZA) + (size_t)row0 * 512, 512, (const bf16_t*)(p.ws + W_WAO) + ((size_t)layer * 1024 + col0) * 512, 512, 128, lds);
; #pragma unroll
;   for (int mi = 0; mi < 4; ++mi)
; #pragma unroll
;     for (int ni = 0; ni < 4; ++ni)
; #pragma unroll
;       for (int j = 0; j < 4; ++j) acc[mi][ni][j] *= (float)((gpv[mi][ni] >> (8 * j)) & 255u) / fmaxf((float)((gav[mi][ni] >> (8 * j)) & 255u), 1.f);
	s_add_u32 s10, s97, s8
	v_readlane_b32 s5, v240, 45
	s_addc_u32 s11, s5, s9
	v_ashrrev_i32_e32 v100, 3, v106
	v_lshrrev_b32_e32 v0, 4, v106
	v_readlane_b32 s8, v240, 33
	v_ashrrev_i32_e32 v101, 31, v100
	v_xor_b32_e32 v0, v0, v106
	v_readlane_b32 s9, v240, 34
	s_add_u32 s8, s8, s12
	v_lshlrev_b64 v[102:103], 10, v[100:101]
	v_lshlrev_b32_e32 v0, 4, v0
	s_addc_u32 s9, s9, s13
	v_lshl_add_u64 v[102:103], s[10:11], 0, v[102:103]
	v_and_b32_e32 v0, 0x70, v0
	v_lshlrev_b32_e32 v107, 9, v100
	v_lshl_add_u64 v[102:103], v[102:103], 0, v[0:1]
	v_lshl_add_u64 v[104:105], s[8:9], 0, v[0:1]
	v_lshlrev_b32_e32 v106, 4, v106
	v_and_b32_e32 v0, 0xfe00, v107
	v_add_u32_e32 v108, 0x4000, v106
	v_readfirstlane_b32 s5, v106
	v_lshlrev_b32_e32 v0, 1, v0
	s_mov_b32 m0, s5
	v_lshl_add_u64 v[100:101], v[104:105], 0, v[0:1]
	v_readfirstlane_b32 s5, v108
	v_add_u32_e32 v0, 0x1000, v106
	global_load_lds_dwordx4 v[102:103], off
	s_mov_b32 m0, s5
	v_readfirstlane_b32 s5, v0
	v_add_u32_e32 v0, 0x4000, v107
	v_and_b32_e32 v0, 0xfe00, v0
	global_load_lds_dwordx4 v[100:101], off
	v_lshl_add_u64 v[100:101], v[102:103], 0, s[40:41]
	s_mov_b32 m0, s5
	v_lshlrev_b32_e32 v0, 1, v0
	global_load_lds_dwordx4 v[100:101], off
	v_lshl_add_u64 v[100:101], v[104:105], 0, v[0:1]
	v_add_u32_e32 v0, 0x5000, v106
	s_mov_b64 s[30:31], 0x100
	v_readfirstlane_b32 s5, v0
	v_add_u32_e32 v0, 0x2000, v106
	s_mov_b32 m0, s5
	v_readfirstlane_b32 s5, v0
	v_bitop3_b32 v0, v107, s33, v167 bitop3:0x6c
	global_load_lds_dwordx4 v[100:101], off
	v_lshl_add_u64 v[100:101], v[102:103], 0, s[42:43]
	s_mov_b32 m0, s5
	v_lshlrev_b32_e32 v0, 1, v0
	global_load_lds_dwordx4 v[100:101], off
	v_lshl_add_u64 v[100:101], v[104:105], 0, v[0:1]
	v_add_u32_e32 v0, 0x6000, v106
	s_nop 0
	v_readfirstlane_b32 s5, v0
	v_add_u32_e32 v0, 0x3000, v106
	s_mov_b32 m0, s5
	v_readfirstlane_b32 s5, v0
	v_add_u32_e32 v0, 0xc000, v107
	v_and_b32_e32 v0, 0xfe00, v0
	global_load_lds_dwordx4 v[100:101], off
	v_lshl_add_u64 v[100:101], v[102:103], 0, s[50:51]
	s_mov_b32 m0, s5
	v_lshlrev_b32_e32 v0, 1, v0
	global_load_lds_dwordx4 v[100:101], off
	v_lshl_add_u64 v[100:101], v[104:105], 0, v[0:1]
	v_add_u32_e32 v0, 0x7000, v106
	v_cvt_f32_ubyte2_e32 v104, v38
	v_readfirstlane_b32 s5, v0
	s_mov_b32 m0, s5
	v_cvt_f32_ubyte0_e32 v0, v46
	global_load_lds_dwordx4 v[100:101], off
	v_max_f32_e32 v100, 1.0, v0
	v_cvt_f32_ubyte1_e32 v0, v46
	v_max_f32_e32 v101, 1.0, v0
	v_cvt_f32_ubyte2_e32 v0, v46
	v_max_f32_e32 v102, 1.0, v0
	v_cvt_f32_ubyte3_e32 v0, v46
	v_max_f32_e32 v103, 1.0, v0
	v_cvt_f32_ubyte0_e32 v0, v38
	v_cvt_f32_ubyte1_e32 v46, v38
	v_cvt_f32_ubyte3_e32 v38, v38
	v_rcp_f32_e32 v105, v103
	s_nop 0
	v_mul_f32_e32 v105, v38, v105
	v_rcp_f32_e32 v38, v102
	s_nop 0
	v_mul_f32_e32 v104, v104, v38
	v_pk_mul_f32 v[12:13], v[104:105], v[12:13]
	v_rcp_f32_e32 v38, v101
	s_nop 0
	v_mul_f32_e32 v107, v46, v38
	v_rcp_f32_e32 v38, v100
	s_nop 0
	v_mul_f32_e32 v106, v0, v38
	v_cvt_f32_ubyte0_e32 v0, v47
	v_max_f32_e32 v104, 1.0, v0
	v_cvt_f32_ubyte1_e32 v0, v47
	v_max_f32_e32 v105, 1.0, v0
	v_cvt_f32_ubyte2_e32 v0, v47
	v_pk_mul_f32 v[10:11], v[106:107], v[10:11]
	v_max_f32_e32 v106, 1.0, v0
	v_cvt_f32_ubyte3_e32 v0, v47
	v_max_f32_e32 v107, 1.0, v0
	v_cvt_f32_ubyte0_e32 v0, v39
	v_cvt_f32_ubyte1_e32 v46, v39
	v_cvt_f32_ubyte2_e32 v38, v39
	v_cvt_f32_ubyte3_e32 v39, v39
	v_rcp_f32_e32 v47, v107
	s_nop 0
	v_mul_f32_e32 v39, v39, v47
	v_rcp_f32_e32 v47, v106
	s_nop 0
	v_mul_f32_e32 v38, v38, v47
	v_pk_mul_f32 v[24:25], v[38:39], v[24:25]
	v_cvt_f32_ubyte3_e32 v39, v40
	v_cvt_f32_ubyte2_e32 v38, v40
	v_rcp_f32_e32 v47, v105
	s_nop 0
	v_mul_f32_e32 v47, v46, v47
	v_rcp_f32_e32 v46, v104
	s_nop 0
	v_mul_f32_e32 v46, v0, v46
	v_cvt_f32_ubyte0_e32 v0, v48
	v_max_f32_e32 v108, 1.0, v0
	v_cvt_f32_ubyte1_e32 v0, v48
	v_max_f32_e32 v109, 1.0, v0
	v_cvt_f32_ubyte2_e32 v0, v48
	v_max_f32_e32 v110, 1.0, v0
	v_cvt_f32_ubyte3_e32 v0, v48
	v_max_f32_e32 v111, 1.0, v0
	v_pk_mul_f32 v[22:23], v[46:47], v[22:23]
	v_cvt_f32_ubyte0_e32 v0, v40
	v_cvt_f32_ubyte1_e32 v46, v40
	v_rcp_f32_e32 v40, v111
	s_nop 0
	v_mul_f32_e32 v39, v39, v40
	v_rcp_f32_e32 v40, v110
	s_nop 0
	v_mul_f32_e32 v38, v38, v40
	v_pk_mul_f32 v[32:33], v[38:39], v[32:33]
	v_cvt_f32_ubyte1_e32 v38, v41
	v_cvt_f32_ubyte2_e32 v39, v41
	v_rcp_f32_e32 v40, v109
	s_nop 0
	v_mul_f32_e32 v47, v46, v40
	v_rcp_f32_e32 v40, v108
	s_nop 0
	v_mul_f32_e32 v46, v0, v40
	v_cvt_f32_ubyte0_e32 v0, v49
	v_max_f32_e32 v112, 1.0, v0
	v_cvt_f32_ubyte1_e32 v0, v49
	v_max_f32_e32 v113, 1.0, v0
	v_cvt_f32_ubyte2_e32 v0, v49
	v_max_f32_e32 v114, 1.0, v0
	v_cvt_f32_ubyte3_e32 v0, v49
	v_max_f32_e32 v115, 1.0, v0
	v_cvt_f32_ubyte3_e32 v40, v41
	v_cvt_f32_ubyte0_e32 v0, v41
	v_pk_mul_f32 v[30:31], v[46:47], v[30:31]
	v_rcp_f32_e32 v41, v115
	s_nop 0
	v_mul_f32_e32 v41, v40, v41
	v_rcp_f32_e32 v40, v114
	s_nop 0
	v_mul_f32_e32 v40, v39, v40
	v_pk_mul_f32 v[40:41], v[40:41], v[96:97]
	v_rcp_f32_e32 v39, v113
	s_nop 0
	v_mul_f32_e32 v39, v38, v39
	v_rcp_f32_e32 v38, v112
	s_nop 0
	v_mul_f32_e32 v38, v0, v38
	v_cvt_f32_ubyte0_e32 v0, v58
	v_pk_mul_f32 v[38:39], v[38:39], v[94:95]
	v_max_f32_e32 v94, 1.0, v0
	v_cvt_f32_ubyte1_e32 v0, v58
	v_max_f32_e32 v95, 1.0, v0
	v_cvt_f32_ubyte2_e32 v0, v58
	v_max_f32_e32 v96, 1.0, v0
	v_cvt_f32_ubyte3_e32 v0, v58
	v_max_f32_e32 v97, 1.0, v0
	v_cvt_f32_ubyte3_e32 v48, v54
	v_cvt_f32_ubyte0_e32 v0, v54
	v_cvt_f32_ubyte1_e32 v46, v54
	v_cvt_f32_ubyte2_e32 v47, v54
	v_rcp_f32_e32 v49, v97
	s_nop 0
	v_mul_f32_e32 v49, v48, v49
	v_rcp_f32_e32 v48, v96
	s_nop 0
	v_mul_f32_e32 v48, v47, v48
	v_pk_mul_f32 v[48:49], v[48:49], v[92:93]
	v_rcp_f32_e32 v47, v95
	s_nop 0
	v_mul_f32_e32 v47, v46, v47
; DI void phaseD_tile(const P& p, int layer, int mt, int nt, char* lds) {
;     ...
; #pragma unroll
;   for (int mi = 0; mi < 4; ++mi)
; #pragma unroll
;     for (int ni = 0; ni < 4; ++ni)
; #pragma unroll
;       for (int j = 0; j < 4; ++j) acc[mi][ni][j] *= (float)((gpv[mi][ni] >> (8 * j)) & 255u) / fmaxf((float)((gav[mi][ni] >> (8 * j)) & 255u), 1.f);
	v_rcp_f32_e32 v46, v94
	s_nop 0
	v_mul_f32_e32 v46, v0, v46
	v_cvt_f32_ubyte0_e32 v0, v59
	v_pk_mul_f32 v[46:47], v[46:47], v[90:91]
	v_max_f32_e32 v90, 1.0, v0
	v_cvt_f32_ubyte1_e32 v0, v59
	v_max_f32_e32 v91, 1.0, v0
	v_cvt_f32_ubyte2_e32 v0, v59
	v_max_f32_e32 v92, 1.0, v0
	v_cvt_f32_ubyte3_e32 v0, v59
	v_max_f32_e32 v93, 1.0, v0
	v_cvt_f32_ubyte0_e32 v0, v55
	v_cvt_f32_ubyte1_e32 v58, v55
	v_cvt_f32_ubyte2_e32 v54, v55
	v_cvt_f32_ubyte3_e32 v55, v55
	v_rcp_f32_e32 v59, v93
	s_nop 0
	v_mul_f32_e32 v55, v55, v59
	v_rcp_f32_e32 v59, v92
	s_nop 0
	v_mul_f32_e32 v54, v54, v59
	v_pk_mul_f32 v[64:65], v[54:55], v[64:65]
	v_cvt_f32_ubyte3_e32 v55, v56
	v_cvt_f32_ubyte2_e32 v54, v56
	v_rcp_f32_e32 v59, v91
	s_nop 0
	v_mul_f32_e32 v59, v58, v59
	v_rcp_f32_e32 v58, v90
	s_nop 0
	v_mul_f32_e32 v58, v0, v58
	v_cvt_f32_ubyte0_e32 v0, v60
	v_max_f32_e32 v116, 1.0, v0
	v_cvt_f32_ubyte1_e32 v0, v60
	v_max_f32_e32 v117, 1.0, v0
	v_cvt_f32_ubyte2_e32 v0, v60
	v_max_f32_e32 v118, 1.0, v0
	v_cvt_f32_ubyte3_e32 v0, v60
	v_max_f32_e32 v119, 1.0, v0
	v_pk_mul_f32 v[62:63], v[58:59], v[62:63]
	v_cvt_f32_ubyte0_e32 v0, v56
	v_cvt_f32_ubyte1_e32 v58, v56
	v_rcp_f32_e32 v56, v119
	s_nop 0
	v_mul_f32_e32 v55, v55, v56
	v_rcp_f32_e32 v56, v118
	s_nop 0
	v_mul_f32_e32 v54, v54, v56
	v_pk_mul_f32 v[72:73], v[54:55], v[72:73]
	v_cvt_f32_ubyte1_e32 v54, v57
	v_cvt_f32_ubyte2_e32 v55, v57
	v_rcp_f32_e32 v56, v117
	s_nop 0
	v_mul_f32_e32 v59, v58, v56
	v_rcp_f32_e32 v56, v116
	s_nop 0
	v_mul_f32_e32 v58, v0, v56
	v_cvt_f32_ubyte0_e32 v0, v61
	v_max_f32_e32 v120, 1.0, v0
	v_cvt_f32_ubyte1_e32 v0, v61
	v_max_f32_e32 v121, 1.0, v0
	v_cvt_f32_ubyte2_e32 v0, v61
	v_max_f32_e32 v122, 1.0, v0
	v_cvt_f32_ubyte3_e32 v0, v61
	v_max_f32_e32 v123, 1.0, v0
	v_cvt_f32_ubyte3_e32 v56, v57
	v_cvt_f32_ubyte0_e32 v0, v57
	v_pk_mul_f32 v[70:71], v[58:59], v[70:71]
	v_rcp_f32_e32 v57, v123
	s_nop 0
	v_mul_f32_e32 v57, v56, v57
	v_rcp_f32_e32 v56, v122
	s_nop 0
	v_mul_f32_e32 v56, v55, v56
	v_pk_mul_f32 v[56:57], v[56:57], v[88:89]
	v_rcp_f32_e32 v55, v121
	s_nop 0
	v_mul_f32_e32 v55, v54, v55
	v_rcp_f32_e32 v54, v120
	s_nop 0
	v_mul_f32_e32 v54, v0, v54
	v_cvt_f32_ubyte0_e32 v0, v18
	v_pk_mul_f32 v[54:55], v[54:55], v[86:87]
	v_max_f32_e32 v86, 1.0, v0
	v_cvt_f32_ubyte1_e32 v0, v18
	v_max_f32_e32 v87, 1.0, v0
	v_cvt_f32_ubyte2_e32 v0, v18
	v_max_f32_e32 v88, 1.0, v0
	v_cvt_f32_ubyte3_e32 v0, v18
	v_max_f32_e32 v89, 1.0, v0
	v_cvt_f32_ubyte0_e32 v0, v14
	v_cvt_f32_ubyte1_e32 v18, v14
	v_cvt_f32_ubyte2_e32 v58, v14
	v_cvt_f32_ubyte3_e32 v14, v14
	v_rcp_f32_e32 v59, v89
	s_nop 0
	v_mul_f32_e32 v61, v14, v59
	v_rcp_f32_e32 v14, v88
	s_nop 0
	v_mul_f32_e32 v60, v58, v14
	v_pk_mul_f32 v[60:61], v[60:61], v[84:85]
	v_rcp_f32_e32 v14, v87
	s_nop 0
	v_mul_f32_e32 v59, v18, v14
	v_rcp_f32_e32 v14, v86
	s_nop 0
	v_mul_f32_e32 v58, v0, v14
	v_cvt_f32_ubyte0_e32 v0, v19
	v_pk_mul_f32 v[58:59], v[58:59], v[82:83]
	v_max_f32_e32 v82, 1.0, v0
	v_cvt_f32_ubyte1_e32 v0, v19
	v_max_f32_e32 v83, 1.0, v0
	v_cvt_f32_ubyte2_e32 v0, v19
	v_max_f32_e32 v84, 1.0, v0
	v_cvt_f32_ubyte3_e32 v0, v19
	v_max_f32_e32 v85, 1.0, v0
	v_cvt_f32_ubyte0_e32 v0, v15
	v_cvt_f32_ubyte1_e32 v18, v15
	v_cvt_f32_ubyte2_e32 v14, v15
	v_cvt_f32_ubyte3_e32 v15, v15
	v_rcp_f32_e32 v19, v85
	s_nop 0
	v_mul_f32_e32 v15, v15, v19
	v_rcp_f32_e32 v19, v84
	s_nop 0
	v_mul_f32_e32 v14, v14, v19
	v_pk_mul_f32 v[80:81], v[14:15], v[80:81]
	v_cvt_f32_ubyte3_e32 v15, v16
	v_cvt_f32_ubyte2_e32 v14, v16
	v_rcp_f32_e32 v19, v83
	s_nop 0
	v_mul_f32_e32 v19, v18, v19
	v_rcp_f32_e32 v18, v82
	s_nop 0
	v_mul_f32_e32 v18, v0, v18
	v_cvt_f32_ubyte0_e32 v0, v20
	v_max_f32_e32 v124, 1.0, v0
	v_cvt_f32_ubyte1_e32 v0, v20
	v_max_f32_e32 v125, 1.0, v0
	v_cvt_f32_ubyte2_e32 v0, v20
	v_max_f32_e32 v126, 1.0, v0
	v_cvt_f32_ubyte3_e32 v0, v20
	v_max_f32_e32 v127, 1.0, v0
	v_pk_mul_f32 v[78:79], v[18:19], v[78:79]
	v_cvt_f32_ubyte0_e32 v0, v16
	v_cvt_f32_ubyte1_e32 v18, v16
	v_rcp_f32_e32 v16, v127
	s_nop 0
	v_mul_f32_e32 v15, v15, v16
	v_rcp_f32_e32 v16, v126
	s_nop 0
	v_mul_f32_e32 v14, v14, v16
	v_pk_mul_f32 v[76:77], v[14:15], v[76:77]
	v_cvt_f32_ubyte1_e32 v14, v17
	v_cvt_f32_ubyte2_e32 v15, v17
	v_rcp_f32_e32 v16, v125
	s_nop 0
	v_mul_f32_e32 v19, v18, v16
	v_rcp_f32_e32 v16, v124
	s_nop 0
	v_mul_f32_e32 v18, v0, v16
	v_cvt_f32_ubyte0_e32 v0, v21
	v_max_f32_e32 v128, 1.0, v0
	v_cvt_f32_ubyte1_e32 v0, v21
	v_max_f32_e32 v129, 1.0, v0
	v_cvt_f32_ubyte2_e32 v0, v21
	v_max_f32_e32 v130, 1.0, v0
	v_cvt_f32_ubyte3_e32 v0, v21
	v_max_f32_e32 v131, 1.0, v0
	v_cvt_f32_ubyte3_e32 v16, v17
	v_cvt_f32_ubyte0_e32 v0, v17
	v_pk_mul_f32 v[74:75], v[18:19], v[74:75]
	v_rcp_f32_e32 v17, v131
	s_nop 0
	v_mul_f32_e32 v17, v16, v17
	v_rcp_f32_e32 v16, v130
	s_nop 0
	v_mul_f32_e32 v16, v15, v16
	v_pk_mul_f32 v[16:17], v[16:17], v[68:69]
	v_rcp_f32_e32 v15, v129
	s_nop 0
	v_mul_f32_e32 v15, v14, v15
	v_rcp_f32_e32 v14, v128
	s_nop 0
	v_mul_f32_e32 v14, v0, v14
	v_cvt_f32_ubyte0_e32 v0, v6
	v_pk_mul_f32 v[14:15], v[14:15], v[66:67]
	v_max_f32_e32 v66, 1.0, v0
	v_cvt_f32_ubyte1_e32 v0, v6
	v_max_f32_e32 v67, 1.0, v0
	v_cvt_f32_ubyte2_e32 v0, v6
	v_max_f32_e32 v68, 1.0, v0
	v_cvt_f32_ubyte3_e32 v0, v6
	v_max_f32_e32 v69, 1.0, v0
	v_cvt_f32_ubyte0_e32 v0, v2
	v_cvt_f32_ubyte1_e32 v6, v2
	v_cvt_f32_ubyte2_e32 v18, v2
	v_cvt_f32_ubyte3_e32 v2, v2
	v_rcp_f32_e32 v19, v69
	s_nop 0
	v_mul_f32_e32 v21, v2, v19
	v_rcp_f32_e32 v2, v68
	s_nop 0
	v_mul_f32_e32 v20, v18, v2
	v_pk_mul_f32 v[20:21], v[20:21], v[52:53]
	v_rcp_f32_e32 v2, v67
	s_nop 0
	v_mul_f32_e32 v19, v6, v2
	v_rcp_f32_e32 v2, v66
	s_nop 0
	v_mul_f32_e32 v18, v0, v2
	v_cvt_f32_ubyte0_e32 v0, v7
	v_max_f32_e32 v52, 1.0, v0
; DI int tidx() { int t = __builtin_amdgcn_workitem_id_x(); asm volatile("" : "+v"(t)); return t; }
; DI void gemm_tile(const bf16_t* __restrict__ A, int lda, const bf16_t* __restrict__ Bt, int ldb, int bvalid, int K, f32x4 (&acc)[4][4], char* lds, bool preloaded = false) {
;   const int tid = tidx(), lane = tid & 63, wave = __builtin_amdgcn_readfirstlane(tid >> 6);
;   const int wm = wave >> 1, wn = wave & 1;
;   const int lr = tid >> 3, lc = tid & 7;
;   const int fr = lane & 15, fq = lane >> 4;
;   const int fx = (fr >> 1) & 7;
;   const bf16_t* ap = A + (size_t)lr * lda + ((lc ^ ((lr >> 1) & 7)) << 3);
;   const bf16_t* bp = Bt + ((lc ^ ((lr >> 1) & 7)) << 3);
;   typedef __attribute__((address_space(1))) const unsigned gptr_t;
;   typedef __attribute__((address_space(3))) unsigned lptr_t;
;   const unsigned lbase = (unsigned)(size_t)lds + (unsigned)tid * 16u;
;     ...
;   auto compute = [&](int st) {
;     const char* base = lds + st * 32768;
;     bf16x8 af[2][4], bfr[2][4];
; #pragma unroll
;     for (int s = 0; s < 2; ++s) {
;       const int ch = ((4 * s + fq) ^ fx) << 4;
; #pragma unroll
;       for (int mi = 0; mi < 4; ++mi) af[s][mi] = *(const bf16x8*)(base + (wm * 64 + mi * 16 + fr) * 128 + ch);
; #pragma unroll
;       for (int ni = 0; ni < 4; ++ni) bfr[s][ni] = *(const bf16x8*)(base + 16384 + (wn * 64 + ni * 16 + fr) * 128 + ch);
;     }
;     __builtin_amdgcn_s_setprio(1);
; #pragma unroll
;     for (int s = 0; s < 2; ++s)
; #pragma unroll
;       for (int mi = 0; mi < 4; ++mi)
; #pragma unroll
;         for (int ni = 0; ni < 4; ++ni) acc[mi][ni] = MFMA16(af[s][mi], bfr[s][ni], acc[mi][ni]);
;     __builtin_amdgcn_s_setprio(0);
;   };
;   const int nk = K >> 6;
;   if (!preloaded) { GLDS(0, 0) }
;   __syncthreads();
;   for (int kt = 0; kt < nk; ++kt) {
;     if (kt + 1 < nk) { GLDS((kt + 1) & 1, (kt + 1) << 6) }
; DI void phaseD_tile(const P& p, int layer, int mt, int nt, char* lds) {
;     ...
; #pragma unroll
;   for (int mi = 0; mi < 4; ++mi)
; #pragma unroll
;     for (int ni = 0; ni < 4; ++ni)
; #pragma unroll
;       for (int j = 0; j < 4; ++j) acc[mi][ni][j] *= (float)((gpv[mi][ni] >> (8 * j)) & 255u) / fmaxf((float)((gav[mi][ni] >> (8 * j)) & 255u), 1.f);
;   gemm_tile((const bf16_t*)(p.ws + W_ZA) + (size_t)row0 * 512, 512, (const bf16_t*)(p.ws + W_WAO) + ((size_t)layer * 1024 + col0) * 512, 512, 128, 512, acc, lds, true);
	v_cvt_f32_ubyte1_e32 v0, v7
	v_max_f32_e32 v53, 1.0, v0
	v_cvt_f32_ubyte2_e32 v0, v7
	v_max_f32_e32 v132, 1.0, v0
	v_cvt_f32_ubyte3_e32 v0, v7
	v_max_f32_e32 v133, 1.0, v0
	v_cvt_f32_ubyte0_e32 v0, v3
	v_cvt_f32_ubyte1_e32 v6, v3
	v_cvt_f32_ubyte2_e32 v2, v3
	v_cvt_f32_ubyte3_e32 v3, v3
	v_pk_mul_f32 v[18:19], v[18:19], v[50:51]
	v_rcp_f32_e32 v7, v133
	s_nop 0
	v_mul_f32_e32 v3, v3, v7
	v_rcp_f32_e32 v7, v132
	s_nop 0
	v_mul_f32_e32 v2, v2, v7
	v_pk_mul_f32 v[44:45], v[2:3], v[44:45]
	v_cvt_f32_ubyte3_e32 v3, v4
	v_cvt_f32_ubyte2_e32 v2, v4
	v_rcp_f32_e32 v7, v53
	s_nop 0
	v_mul_f32_e32 v7, v6, v7
	v_rcp_f32_e32 v6, v52
	s_nop 0
	v_mul_f32_e32 v6, v0, v6
	v_cvt_f32_ubyte0_e32 v0, v8
	v_max_f32_e32 v134, 1.0, v0
	v_cvt_f32_ubyte1_e32 v0, v8
	v_max_f32_e32 v135, 1.0, v0
	v_cvt_f32_ubyte2_e32 v0, v8
	v_max_f32_e32 v136, 1.0, v0
	v_cvt_f32_ubyte3_e32 v0, v8
	v_max_f32_e32 v137, 1.0, v0
	v_pk_mul_f32 v[42:43], v[6:7], v[42:43]
	v_cvt_f32_ubyte0_e32 v0, v4
	v_cvt_f32_ubyte1_e32 v6, v4
	v_rcp_f32_e32 v4, v137
	s_nop 0
	v_mul_f32_e32 v3, v3, v4
	v_rcp_f32_e32 v4, v136
	s_nop 0
	v_mul_f32_e32 v2, v2, v4
	v_pk_mul_f32 v[36:37], v[2:3], v[36:37]
	v_cvt_f32_ubyte1_e32 v2, v5
	v_cvt_f32_ubyte2_e32 v3, v5
	v_rcp_f32_e32 v4, v135
	s_nop 0
	v_mul_f32_e32 v7, v6, v4
	v_rcp_f32_e32 v4, v134
	s_nop 0
	v_mul_f32_e32 v6, v0, v4
	v_cvt_f32_ubyte0_e32 v0, v9
	v_max_f32_e32 v138, 1.0, v0
	v_cvt_f32_ubyte1_e32 v0, v9
	v_max_f32_e32 v139, 1.0, v0
	v_cvt_f32_ubyte2_e32 v0, v9
	v_max_f32_e32 v140, 1.0, v0
	v_cvt_f32_ubyte3_e32 v0, v9
	v_max_f32_e32 v141, 1.0, v0
	v_cvt_f32_ubyte3_e32 v4, v5
	v_cvt_f32_ubyte0_e32 v0, v5
	v_pk_mul_f32 v[34:35], v[6:7], v[34:35]
	v_rcp_f32_e32 v5, v141
	s_nop 0
	v_mul_f32_e32 v5, v4, v5
	v_rcp_f32_e32 v4, v140
	s_nop 0
	v_mul_f32_e32 v4, v3, v4
	v_pk_mul_f32 v[4:5], v[4:5], v[28:29]
	v_rcp_f32_e32 v3, v139
	s_nop 0
	v_mul_f32_e32 v3, v2, v3
	v_rcp_f32_e32 v2, v138
	s_nop 0
	v_mul_f32_e32 v2, v0, v2
	v_pk_mul_f32 v[2:3], v[2:3], v[26:27]
	v_mov_b32_e32 v26, v158
	s_waitcnt vmcnt(0) lgkmcnt(0)
	v_ashrrev_i32_e32 v8, 3, v26
	v_lshrrev_b32_e32 v0, 4, v26
	v_ashrrev_i32_e32 v9, 31, v8
	v_xor_b32_e32 v0, v0, v26
	v_lshlrev_b64 v[6:7], 10, v[8:9]
	v_lshlrev_b32_e32 v0, 4, v0
	v_readfirstlane_b32 s5, v26
	v_lshl_add_u64 v[6:7], s[10:11], 0, v[6:7]
	v_and_b32_e32 v0, 0x70, v0
	v_lshl_add_u64 v[6:7], v[6:7], 0, v[0:1]
	v_lshl_add_u64 v[50:51], s[8:9], 0, v[0:1]
	s_lshl_b32 s8, s5, 7
	v_lshlrev_b32_e32 v0, 7, v26
	s_lshl_b32 s5, s5, 6
	v_bfe_u32 v27, v26, 4, 2
	v_bfe_u32 v29, v26, 1, 3
	s_and_b32 s8, s8, 0x2000
	v_and_b32_e32 v0, 0x780, v0
	s_and_b32 s5, s5, 0xffffe000
	v_lshlrev_b32_e32 v156, 4, v26
	v_or_b32_e32 v157, s8, v0
	v_or_b32_e32 v179, s5, v0
	v_bitop3_b32 v0, v27, v29, 4 bitop3:0x36
	v_lshrrev_b32_e32 v28, 1, v26
	v_lshlrev_b32_e32 v220, 4, v0
	v_lshlrev_b32_e32 v0, 9, v8
	v_add_u32_e32 v143, 0x8000, v156
	v_bitop3_b32 v9, v28, v27, 7 bitop3:0x6c
	v_and_b32_e32 v26, 0xfe00, v0
	v_add_u32_e32 v8, 0x4000, v0
	v_bitop3_b32 v146, v0, s33, v167 bitop3:0x6c
	v_add_u32_e32 v0, 0xc000, v0
	v_readfirstlane_b32 s13, v143
	v_lshlrev_b32_e32 v145, 4, v9
	v_and_b32_e32 v28, 0xfe00, v8
	v_and_b32_e32 v148, 0xfe00, v0
	v_lshl_add_u64 v[8:9], v[6:7], 0, s[38:39]
	v_add_u32_e32 v142, 0xc000, v156
	s_mov_b32 m0, s13
	v_lshlrev_b32_e32 v0, 1, v26
	s_barrier
	global_load_lds_dwordx4 v[8:9], off
	v_lshl_add_u64 v[8:9], v[50:51], 0, v[0:1]
	v_readfirstlane_b32 s12, v142
	v_add_u32_e32 v144, 0x9000, v156
	v_lshl_add_u64 v[26:27], v[8:9], 0, s[38:39]
	s_mov_b32 m0, s12
	v_readfirstlane_b32 s21, v144
	global_load_lds_dwordx4 v[26:27], off
	v_lshl_add_u64 v[26:27], v[6:7], 0, s[58:59]
	s_mov_b32 m0, s21
	v_lshlrev_b32_e32 v0, 1, v28
	global_load_lds_dwordx4 v[26:27], off
	v_lshl_add_u64 v[26:27], v[50:51], 0, v[0:1]
	v_add_u32_e32 v0, 0xd000, v156
	v_lshl_add_u64 v[28:29], v[26:27], 0, s[38:39]
	v_readfirstlane_b32 s5, v0
	v_add_u32_e32 v0, 0xa000, v156
	s_mov_b32 m0, s5
	v_readfirstlane_b32 s8, v0
	global_load_lds_dwordx4 v[28:29], off
	v_lshl_add_u64 v[28:29], v[6:7], 0, s[62:63]
	s_mov_b32 m0, s8
	v_lshlrev_b32_e32 v0, 1, v146
	global_load_lds_dwordx4 v[28:29], off
	v_lshl_add_u64 v[28:29], v[50:51], 0, v[0:1]
	v_add_u32_e32 v0, 0xe000, v156
	v_lshl_add_u64 v[146:147], v[28:29], 0, s[38:39]
	v_readfirstlane_b32 s9, v0
	v_add_u32_e32 v0, 0xb000, v156
	s_mov_b32 m0, s9
	v_readfirstlane_b32 s10, v0
	v_lshlrev_b32_e32 v0, 1, v148
	v_lshl_add_u64 v[50:51], v[50:51], 0, v[0:1]
	v_add_u32_e32 v0, 0xf000, v156
	global_load_lds_dwordx4 v[146:147], off
	v_lshl_add_u64 v[146:147], v[6:7], 0, s[68:69]
	s_mov_b32 m0, s10
	v_readfirstlane_b32 s11, v0
	global_load_lds_dwordx4 v[146:147], off
	v_lshl_add_u64 v[146:147], v[50:51], 0, s[38:39]
	s_mov_b32 m0, s11
	v_or_b32_e32 v0, v145, v179
	global_load_lds_dwordx4 v[146:147], off
	v_or_b32_e32 v145, v145, v157
	v_or_b32_e32 v146, v220, v179
	v_or_b32_e32 v147, v220, v157
	ds_read_b128 v[148:151], v0
	ds_read_b128 v[152:155], v0 offset:2048
	ds_read_b128 v[180:183], v0 offset:4096
	ds_read_b128 v[184:187], v0 offset:6144
	ds_read_b128 v[188:191], v145 offset:16384
	ds_read_b128 v[192:195], v145 offset:18432
	ds_read_b128 v[196:199], v145 offset:20480
	ds_read_b128 v[200:203], v145 offset:22528
	ds_read_b128 v[204:207], v146
	ds_read_b128 v[208:211], v146 offset:2048
	ds_read_b128 v[212:215], v146 offset:4096
	ds_read_b128 v[216:219], v146 offset:6144
	ds_read_b128 v[220:223], v147 offset:16384
	ds_read_b128 v[224:227], v147 offset:18432
	ds_read_b128 v[228:231], v147 offset:20480
	ds_read_b128 v[232:235], v147 offset:22528
	s_setprio 1
	s_waitcnt lgkmcnt(8)
; #define MFMA16(a, b, c) __builtin_amdgcn_mfma_f32_16x16x32_bf16((a), (b), (c), 0, 0, 0)
; DI void gemm_tile(const bf16_t* __restrict__ A, int lda, const bf16_t* __restrict__ Bt, int ldb, int bvalid, int K, f32x4 (&acc)[4][4], char* lds, bool preloaded = false) {
;     ...
;   auto compute = [&](int st) {
;     const char* base = lds + st * 32768;
;     bf16x8 af[2][4], bfr[2][4];
; #pragma unroll
;     for (int s = 0; s < 2; ++s) {
;       const int ch = ((4 * s + fq) ^ fx) << 4;
; #pragma unroll
;       for (int mi = 0; mi < 4; ++mi) af[s][mi] = *(const bf16x8*)(base + (wm * 64 + mi * 16 + fr) * 128 + ch);
; #pragma unroll
;       for (int ni = 0; ni < 4; ++ni) bfr[s][ni] = *(const bf16x8*)(base + 16384 + (wn * 64 + ni * 16 + fr) * 128 + ch);
;     }
;     __builtin_amdgcn_s_setprio(1);
; #pragma unroll
;     for (int s = 0; s < 2; ++s)
; #pragma unroll
;       for (int mi = 0; mi < 4; ++mi)
; #pragma unroll
;         for (int ni = 0; ni < 4; ++ni) acc[mi][ni] = MFMA16(af[s][mi], bfr[s][ni], acc[mi][ni]);
;     __builtin_amdgcn_s_setprio(0);
;   };
;   const int nk = K >> 6;
;   if (!preloaded) { GLDS(0, 0) }
;   __syncthreads();
;   for (int kt = 0; kt < nk; ++kt) {
;     if (kt + 1 < nk) { GLDS((kt + 1) & 1, (kt + 1) << 6) }
;     compute(kt & 1);
;     __syncthreads();
;   }
	v_mfma_f32_16x16x32_bf16 v[2:5], v[184:187], v[200:203], v[2:5]
	v_mfma_f32_16x16x32_bf16 v[10:13], v[148:151], v[188:191], v[10:13]
	v_mfma_f32_16x16x32_bf16 v[22:25], v[148:151], v[192:195], v[22:25]
	v_mfma_f32_16x16x32_bf16 v[30:33], v[148:151], v[196:199], v[30:33]
	v_mfma_f32_16x16x32_bf16 v[38:41], v[148:151], v[200:203], v[38:41]
	v_mfma_f32_16x16x32_bf16 v[46:49], v[152:155], v[188:191], v[46:49]
	v_mfma_f32_16x16x32_bf16 v[62:65], v[152:155], v[192:195], v[62:65]
	v_mfma_f32_16x16x32_bf16 v[70:73], v[152:155], v[196:199], v[70:73]
	v_mfma_f32_16x16x32_bf16 v[54:57], v[152:155], v[200:203], v[54:57]
	v_mfma_f32_16x16x32_bf16 v[58:61], v[180:183], v[188:191], v[58:61]
	v_mfma_f32_16x16x32_bf16 v[78:81], v[180:183], v[192:195], v[78:81]
	v_mfma_f32_16x16x32_bf16 v[74:77], v[180:183], v[196:199], v[74:77]
	v_mfma_f32_16x16x32_bf16 v[14:17], v[180:183], v[200:203], v[14:17]
	v_mfma_f32_16x16x32_bf16 v[18:21], v[184:187], v[188:191], v[18:21]
	v_mfma_f32_16x16x32_bf16 v[42:45], v[184:187], v[192:195], v[42:45]
	v_mfma_f32_16x16x32_bf16 v[34:37], v[184:187], v[196:199], v[34:37]
	s_waitcnt lgkmcnt(0)
	v_mfma_f32_16x16x32_bf16 v[2:5], v[216:219], v[232:235], v[2:5]
	v_mfma_f32_16x16x32_bf16 v[10:13], v[204:207], v[220:223], v[10:13]
	v_mfma_f32_16x16x32_bf16 v[22:25], v[204:207], v[224:227], v[22:25]
	v_mfma_f32_16x16x32_bf16 v[30:33], v[204:207], v[228:231], v[30:33]
	v_mfma_f32_16x16x32_bf16 v[38:41], v[204:207], v[232:235], v[38:41]
	v_mfma_f32_16x16x32_bf16 v[46:49], v[208:211], v[220:223], v[46:49]
	v_mfma_f32_16x16x32_bf16 v[62:65], v[208:211], v[224:227], v[62:65]
	v_mfma_f32_16x16x32_bf16 v[70:73], v[208:211], v[228:231], v[70:73]
	v_mfma_f32_16x16x32_bf16 v[54:57], v[208:211], v[232:235], v[54:57]
	v_mfma_f32_16x16x32_bf16 v[58:61], v[212:215], v[220:223], v[58:61]
	v_mfma_f32_16x16x32_bf16 v[78:81], v[212:215], v[224:227], v[78:81]
	v_mfma_f32_16x16x32_bf16 v[74:77], v[212:215], v[228:231], v[74:77]
	v_mfma_f32_16x16x32_bf16 v[14:17], v[212:215], v[232:235], v[14:17]
	v_mfma_f32_16x16x32_bf16 v[18:21], v[216:219], v[220:223], v[18:21]
	v_mfma_f32_16x16x32_bf16 v[42:45], v[216:219], v[224:227], v[42:45]
	v_mfma_f32_16x16x32_bf16 v[34:37], v[216:219], v[228:231], v[34:37]
	s_setprio 0
	v_add_u32_e32 v150, 0x4000, v156
	v_readfirstlane_b32 s25, v156
	v_lshl_add_u64 v[148:149], v[6:7], 0, s[30:31]
	s_mov_b32 m0, s25
	v_readfirstlane_b32 s22, v150
	v_add_u32_e32 v150, 0x1000, v156
	s_waitcnt vmcnt(0)
	s_barrier
	global_load_lds_dwordx4 v[148:149], off
	v_lshl_add_u64 v[148:149], v[8:9], 0, s[30:31]
	s_mov_b32 m0, s22
	v_readfirstlane_b32 s23, v150
	v_add_u32_e32 v150, 0x5000, v156
	global_load_lds_dwordx4 v[148:149], off
	v_lshl_add_u64 v[148:149], v[6:7], 0, s[70:71]
	s_mov_b32 m0, s23
	v_readfirstlane_b32 s24, v150
	v_add_u32_e32 v150, 0x2000, v156
	global_load_lds_dwordx4 v[148:149], off
	v_lshl_add_u64 v[148:149], v[26:27], 0, s[30:31]
	s_mov_b32 m0, s24
	v_readfirstlane_b32 s26, v150
	v_add_u32_e32 v150, 0x6000, v156
	global_load_lds_dwordx4 v[148:149], off
	v_lshl_add_u64 v[148:149], v[6:7], 0, s[92:93]
	s_mov_b32 m0, s26
	v_readfirstlane_b32 s27, v150
	global_load_lds_dwordx4 v[148:149], off
	v_lshl_add_u64 v[148:149], v[28:29], 0, s[30:31]
	s_mov_b32 m0, s27
	s_mov_b64 s[28:29], 0x18100
	v_add_u32_e32 v150, 0x3000, v156
	global_load_lds_dwordx4 v[148:149], off
	v_lshl_add_u64 v[148:149], v[6:7], 0, s[28:29]
	v_readfirstlane_b32 s28, v150
	v_add_u32_e32 v150, 0x7000, v156
	s_mov_b32 m0, s28
	v_readfirstlane_b32 s29, v150
	global_load_lds_dwordx4 v[148:149], off
	v_lshl_add_u64 v[148:149], v[50:51], 0, s[30:31]
	s_mov_b32 m0, s29
	s_nop 0
	global_load_lds_dwordx4 v[148:149], off
	ds_read_b128 v[148:151], v0 offset:32768
	ds_read_b128 v[152:155], v0 offset:34816
	ds_read_b128 v[180:183], v0 offset:36864
	ds_read_b128 v[184:187], v0 offset:38912
	ds_read_b128 v[188:191], v145 offset:49152
	ds_read_b128 v[192:195], v145 offset:51200
	ds_read_b128 v[196:199], v145 offset:53248
	ds_read_b128 v[200:203], v145 offset:55296
	ds_read_b128 v[204:207], v146 offset:32768
	ds_read_b128 v[208:211], v146 offset:34816
	ds_read_b128 v[212:215], v146 offset:36864
	ds_read_b128 v[216:219], v146 offset:38912
	ds_read_b128 v[220:223], v147 offset:49152
	ds_read_b128 v[224:227], v147 offset:51200
	ds_read_b128 v[228:231], v147 offset:53248
	ds_read_b128 v[232:235], v147 offset:55296
	s_setprio 1
	s_waitcnt lgkmcnt(8)
	v_mfma_f32_16x16x32_bf16 v[2:5], v[184:187], v[200:203], v[2:5]
	v_mfma_f32_16x16x32_bf16 v[10:13], v[148:151], v[188:191], v[10:13]
	v_mfma_f32_16x16x32_bf16 v[22:25], v[148:151], v[192:195], v[22:25]
	v_mfma_f32_16x16x32_bf16 v[30:33], v[148:151], v[196:199], v[30:33]
	v_mfma_f32_16x16x32_bf16 v[38:41], v[148:151], v[200:203], v[38:41]
	v_mfma_f32_16x16x32_bf16 v[46:49], v[152:155], v[188:191], v[46:49]
	v_mfma_f32_16x16x32_bf16 v[62:65], v[152:155], v[192:195], v[62:65]
	v_mfma_f32_16x16x32_bf16 v[70:73], v[152:155], v[196:199], v[70:73]
	v_mfma_f32_16x16x32_bf16 v[54:57], v[152:155], v[200:203], v[54:57]
	v_mfma_f32_16x16x32_bf16 v[58:61], v[180:183], v[188:191], v[58:61]
	v_mfma_f32_16x16x32_bf16 v[78:81], v[180:183], v[192:195], v[78:81]
	v_mfma_f32_16x16x32_bf16 v[74:77], v[180:183], v[196:199], v[74:77]
	v_mfma_f32_16x16x32_bf16 v[14:17], v[180:183], v[200:203], v[14:17]
	v_mfma_f32_16x16x32_bf16 v[18:21], v[184:187], v[188:191], v[18:21]
	v_mfma_f32_16x16x32_bf16 v[42:45], v[184:187], v[192:195], v[42:45]
	v_mfma_f32_16x16x32_bf16 v[34:37], v[184:187], v[196:199], v[34:37]
	s_waitcnt lgkmcnt(0)
	v_mfma_f32_16x16x32_bf16 v[2:5], v[216:219], v[232:235], v[2:5]
	v_mfma_f32_16x16x32_bf16 v[10:13], v[204:207], v[220:223], v[10:13]
	v_mfma_f32_16x16x32_bf16 v[22:25], v[204:207], v[224:227], v[22:25]
	v_mfma_f32_16x16x32_bf16 v[30:33], v[204:207], v[228:231], v[30:33]
	v_mfma_f32_16x16x32_bf16 v[38:41], v[204:207], v[232:235], v[38:41]
	v_mfma_f32_16x16x32_bf16 v[46:49], v[208:211], v[220:223], v[46:49]
	v_mfma_f32_16x16x32_bf16 v[62:65], v[208:211], v[224:227], v[62:65]
	v_mfma_f32_16x16x32_bf16 v[70:73], v[208:211], v[228:231], v[70:73]
	v_mfma_f32_16x16x32_bf16 v[54:57], v[208:211], v[232:235], v[54:57]
	v_mfma_f32_16x16x32_bf16 v[58:61], v[212:215], v[220:223], v[58:61]
	v_mfma_f32_16x16x32_bf16 v[78:81], v[212:215], v[224:227], v[78:81]
	v_mfma_f32_16x16x32_bf16 v[74:77], v[212:215], v[228:231], v[74:77]
	v_mfma_f32_16x16x32_bf16 v[14:17], v[212:215], v[232:235], v[14:17]
	v_mfma_f32_16x16x32_bf16 v[18:21], v[216:219], v[220:223], v[18:21]
	v_mfma_f32_16x16x32_bf16 v[42:45], v[216:219], v[224:227], v[42:45]
	v_mfma_f32_16x16x32_bf16 v[34:37], v[216:219], v[228:231], v[34:37]
	s_setprio 0
	s_mov_b32 m0, s13
	v_lshl_add_u64 v[148:149], v[6:7], 0, s[0:1]
	s_waitcnt vmcnt(0)
	s_barrier
; #define MFMA16(a, b, c) __builtin_amdgcn_mfma_f32_16x16x32_bf16((a), (b), (c), 0, 0, 0)
; DI void gemm_tile(const bf16_t* __restrict__ A, int lda, const bf16_t* __restrict__ Bt, int ldb, int bvalid, int K, f32x4 (&acc)[4][4], char* lds, bool preloaded = false) {
;     ...
;   auto compute = [&](int st) {
;     const char* base = lds + st * 32768;
;     bf16x8 af[2][4], bfr[2][4];
; #pragma unroll
;     for (int s = 0; s < 2; ++s) {
;       const int ch = ((4 * s + fq) ^ fx) << 4;
; #pragma unroll
;       for (int mi = 0; mi < 4; ++mi) af[s][mi] = *(const bf16x8*)(base + (wm * 64 + mi * 16 + fr) * 128 + ch);
; #pragma unroll
;       for (int ni = 0; ni < 4; ++ni) bfr[s][ni] = *(const bf16x8*)(base + 16384 + (wn * 64 + ni * 16 + fr) * 128 + ch);
;     }
;     __builtin_amdgcn_s_setprio(1);
; #pragma unroll
;     for (int s = 0; s < 2; ++s)
; #pragma unroll
;       for (int mi = 0; mi < 4; ++mi)
; #pragma unroll
;         for (int ni = 0; ni < 4; ++ni) acc[mi][ni] = MFMA16(af[s][mi], bfr[s][ni], acc[mi][ni]);
;     __builtin_amdgcn_s_setprio(0);
;   };
;   const int nk = K >> 6;
;   if (!preloaded) { GLDS(0, 0) }
;   __syncthreads();
;   for (int kt = 0; kt < nk; ++kt) {
;     if (kt + 1 < nk) { GLDS((kt + 1) & 1, (kt + 1) << 6) }
;     compute(kt & 1);
;     __syncthreads();
;   }
	global_load_lds_dwordx4 v[148:149], off
	v_lshl_add_u64 v[148:149], v[8:9], 0, s[0:1]
	s_mov_b32 m0, s12
	s_mov_b64 s[30:31], 0x8180
	global_load_lds_dwordx4 v[148:149], off
	v_lshl_add_u64 v[148:149], v[6:7], 0, s[30:31]
	s_mov_b32 m0, s21
	s_mov_b64 s[30:31], 0x10180
	global_load_lds_dwordx4 v[148:149], off
	v_lshl_add_u64 v[148:149], v[26:27], 0, s[0:1]
	s_mov_b32 m0, s5
	s_nop 0
	global_load_lds_dwordx4 v[148:149], off
	v_lshl_add_u64 v[148:149], v[6:7], 0, s[30:31]
	s_mov_b32 m0, s8
	s_mov_b64 s[30:31], 0x18180
	global_load_lds_dwordx4 v[148:149], off
	v_lshl_add_u64 v[148:149], v[28:29], 0, s[0:1]
	s_mov_b32 m0, s9
	s_nop 0
	global_load_lds_dwordx4 v[148:149], off
	v_lshl_add_u64 v[148:149], v[6:7], 0, s[30:31]
	s_mov_b32 m0, s10
	s_nop 0
	global_load_lds_dwordx4 v[148:149], off
	v_lshl_add_u64 v[148:149], v[50:51], 0, s[0:1]
	s_mov_b32 m0, s11
	s_nop 0
	global_load_lds_dwordx4 v[148:149], off
	ds_read_b128 v[148:151], v0
	ds_read_b128 v[152:155], v0 offset:2048
	ds_read_b128 v[180:183], v0 offset:4096
	ds_read_b128 v[184:187], v0 offset:6144
	ds_read_b128 v[188:191], v145 offset:16384
	ds_read_b128 v[192:195], v145 offset:18432
	ds_read_b128 v[196:199], v145 offset:20480
	ds_read_b128 v[200:203], v145 offset:22528
	ds_read_b128 v[204:207], v146
	ds_read_b128 v[208:211], v146 offset:2048
	ds_read_b128 v[212:215], v146 offset:4096
	ds_read_b128 v[216:219], v146 offset:6144
	ds_read_b128 v[220:223], v147 offset:16384
	ds_read_b128 v[224:227], v147 offset:18432
	ds_read_b128 v[228:231], v147 offset:20480
	ds_read_b128 v[232:235], v147 offset:22528
	s_setprio 1
	s_waitcnt lgkmcnt(8)
	v_mfma_f32_16x16x32_bf16 v[2:5], v[184:187], v[200:203], v[2:5]
	v_mfma_f32_16x16x32_bf16 v[10:13], v[148:151], v[188:191], v[10:13]
	v_mfma_f32_16x16x32_bf16 v[22:25], v[148:151], v[192:195], v[22:25]
	v_mfma_f32_16x16x32_bf16 v[30:33], v[148:151], v[196:199], v[30:33]
	v_mfma_f32_16x16x32_bf16 v[38:41], v[148:151], v[200:203], v[38:41]
	v_mfma_f32_16x16x32_bf16 v[46:49], v[152:155], v[188:191], v[46:49]
	v_mfma_f32_16x16x32_bf16 v[62:65], v[152:155], v[192:195], v[62:65]
	v_mfma_f32_16x16x32_bf16 v[70:73], v[152:155], v[196:199], v[70:73]
	v_mfma_f32_16x16x32_bf16 v[54:57], v[152:155], v[200:203], v[54:57]
	v_mfma_f32_16x16x32_bf16 v[58:61], v[180:183], v[188:191], v[58:61]
	v_mfma_f32_16x16x32_bf16 v[78:81], v[180:183], v[192:195], v[78:81]
	v_mfma_f32_16x16x32_bf16 v[74:77], v[180:183], v[196:199], v[74:77]
	v_mfma_f32_16x16x32_bf16 v[14:17], v[180:183], v[200:203], v[14:17]
	v_mfma_f32_16x16x32_bf16 v[18:21], v[184:187], v[188:191], v[18:21]
	v_mfma_f32_16x16x32_bf16 v[42:45], v[184:187], v[192:195], v[42:45]
	v_mfma_f32_16x16x32_bf16 v[34:37], v[184:187], v[196:199], v[34:37]
	s_waitcnt lgkmcnt(0)
	v_mfma_f32_16x16x32_bf16 v[2:5], v[216:219], v[232:235], v[2:5]
	v_mfma_f32_16x16x32_bf16 v[10:13], v[204:207], v[220:223], v[10:13]
	v_mfma_f32_16x16x32_bf16 v[22:25], v[204:207], v[224:227], v[22:25]
	v_mfma_f32_16x16x32_bf16 v[30:33], v[204:207], v[228:231], v[30:33]
	v_mfma_f32_16x16x32_bf16 v[38:41], v[204:207], v[232:235], v[38:41]
	v_mfma_f32_16x16x32_bf16 v[46:49], v[208:211], v[220:223], v[46:49]
	v_mfma_f32_16x16x32_bf16 v[62:65], v[208:211], v[224:227], v[62:65]
	v_mfma_f32_16x16x32_bf16 v[70:73], v[208:211], v[228:231], v[70:73]
	v_mfma_f32_16x16x32_bf16 v[54:57], v[208:211], v[232:235], v[54:57]
	v_mfma_f32_16x16x32_bf16 v[58:61], v[212:215], v[220:223], v[58:61]
	v_mfma_f32_16x16x32_bf16 v[78:81], v[212:215], v[224:227], v[78:81]
	v_mfma_f32_16x16x32_bf16 v[74:77], v[212:215], v[228:231], v[74:77]
	v_mfma_f32_16x16x32_bf16 v[14:17], v[212:215], v[232:235], v[14:17]
	v_mfma_f32_16x16x32_bf16 v[18:21], v[216:219], v[220:223], v[18:21]
	v_mfma_f32_16x16x32_bf16 v[42:45], v[216:219], v[224:227], v[42:45]
	v_mfma_f32_16x16x32_bf16 v[34:37], v[216:219], v[228:231], v[34:37]
	s_setprio 0
	s_mov_b32 m0, s25
	v_lshl_add_u64 v[148:149], v[6:7], 0, s[36:37]
	s_waitcnt vmcnt(0)
	s_barrier
	global_load_lds_dwordx4 v[148:149], off
	v_lshl_add_u64 v[148:149], v[8:9], 0, s[36:37]
	s_mov_b32 m0, s22
	s_mov_b64 s[0:1], 0x8200
	global_load_lds_dwordx4 v[148:149], off
	v_lshl_add_u64 v[148:149], v[6:7], 0, s[0:1]
	s_mov_b32 m0, s23
	s_mov_b64 s[0:1], 0x10200
	global_load_lds_dwordx4 v[148:149], off
	v_lshl_add_u64 v[148:149], v[26:27], 0, s[36:37]
	s_mov_b32 m0, s24
	s_nop 0
	global_load_lds_dwordx4 v[148:149], off
	v_lshl_add_u64 v[148:149], v[6:7], 0, s[0:1]
	s_mov_b32 m0, s26
	s_mov_b64 s[0:1], 0x18200
	global_load_lds_dwordx4 v[148:149], off
	v_lshl_add_u64 v[148:149], v[28:29], 0, s[36:37]
	s_mov_b32 m0, s27
	s_nop 0
	global_load_lds_dwordx4 v[148:149], off
	v_lshl_add_u64 v[148:149], v[6:7], 0, s[0:1]
	s_mov_b32 m0, s28
	s_nop 0
	global_load_lds_dwordx4 v[148:149], off
	v_lshl_add_u64 v[148:149], v[50:51], 0, s[36:37]
	s_mov_b32 m0, s29
	s_nop 0
	global_load_lds_dwordx4 v[148:149], off
	ds_read_b128 v[148:151], v0 offset:32768
	ds_read_b128 v[152:155], v0 offset:34816
	ds_read_b128 v[180:183], v0 offset:36864
	ds_read_b128 v[184:187], v0 offset:38912
	ds_read_b128 v[188:191], v145 offset:49152
	ds_read_b128 v[192:195], v145 offset:51200
	ds_read_b128 v[196:199], v145 offset:53248
	ds_read_b128 v[200:203], v145 offset:55296
	ds_read_b128 v[204:207], v146 offset:32768
	ds_read_b128 v[208:211], v146 offset:34816
	ds_read_b128 v[212:215], v146 offset:36864
	ds_read_b128 v[216:219], v146 offset:38912
	ds_read_b128 v[220:223], v147 offset:49152
	ds_read_b128 v[224:227], v147 offset:51200
	ds_read_b128 v[228:231], v147 offset:53248
	ds_read_b128 v[232:235], v147 offset:55296
	s_setprio 1
	s_waitcnt lgkmcnt(8)
; #define MFMA16(a, b, c) __builtin_amdgcn_mfma_f32_16x16x32_bf16((a), (b), (c), 0, 0, 0)
; DI void gemm_tile(const bf16_t* __restrict__ A, int lda, const bf16_t* __restrict__ Bt, int ldb, int bvalid, int K, f32x4 (&acc)[4][4], char* lds, bool preloaded = false) {
;     ...
;   auto compute = [&](int st) {
;     const char* base = lds + st * 32768;
;     bf16x8 af[2][4], bfr[2][4];
; #pragma unroll
;     for (int s = 0; s < 2; ++s) {
;       const int ch = ((4 * s + fq) ^ fx) << 4;
; #pragma unroll
;       for (int mi = 0; mi < 4; ++mi) af[s][mi] = *(const bf16x8*)(base + (wm * 64 + mi * 16 + fr) * 128 + ch);
; #pragma unroll
;       for (int ni = 0; ni < 4; ++ni) bfr[s][ni] = *(const bf16x8*)(base + 16384 + (wn * 64 + ni * 16 + fr) * 128 + ch);
;     }
;     __builtin_amdgcn_s_setprio(1);
; #pragma unroll
;     for (int s = 0; s < 2; ++s)
; #pragma unroll
;       for (int mi = 0; mi < 4; ++mi)
; #pragma unroll
;         for (int ni = 0; ni < 4; ++ni) acc[mi][ni] = MFMA16(af[s][mi], bfr[s][ni], acc[mi][ni]);
;     __builtin_amdgcn_s_setprio(0);
;   };
;   const int nk = K >> 6;
;   if (!preloaded) { GLDS(0, 0) }
;   __syncthreads();
;   for (int kt = 0; kt < nk; ++kt) {
;     if (kt + 1 < nk) { GLDS((kt + 1) & 1, (kt + 1) << 6) }
;     compute(kt & 1);
;     __syncthreads();
;   }
	v_mfma_f32_16x16x32_bf16 v[2:5], v[184:187], v[200:203], v[2:5]
	v_mfma_f32_16x16x32_bf16 v[10:13], v[148:151], v[188:191], v[10:13]
	v_mfma_f32_16x16x32_bf16 v[22:25], v[148:151], v[192:195], v[22:25]
	v_mfma_f32_16x16x32_bf16 v[30:33], v[148:151], v[196:199], v[30:33]
	v_mfma_f32_16x16x32_bf16 v[38:41], v[148:151], v[200:203], v[38:41]
	v_mfma_f32_16x16x32_bf16 v[46:49], v[152:155], v[188:191], v[46:49]
	v_mfma_f32_16x16x32_bf16 v[62:65], v[152:155], v[192:195], v[62:65]
	v_mfma_f32_16x16x32_bf16 v[70:73], v[152:155], v[196:199], v[70:73]
	v_mfma_f32_16x16x32_bf16 v[54:57], v[152:155], v[200:203], v[54:57]
	v_mfma_f32_16x16x32_bf16 v[58:61], v[180:183], v[188:191], v[58:61]
	v_mfma_f32_16x16x32_bf16 v[78:81], v[180:183], v[192:195], v[78:81]
	v_mfma_f32_16x16x32_bf16 v[74:77], v[180:183], v[196:199], v[74:77]
	v_mfma_f32_16x16x32_bf16 v[14:17], v[180:183], v[200:203], v[14:17]
	v_mfma_f32_16x16x32_bf16 v[18:21], v[184:187], v[188:191], v[18:21]
	v_mfma_f32_16x16x32_bf16 v[42:45], v[184:187], v[192:195], v[42:45]
	v_mfma_f32_16x16x32_bf16 v[34:37], v[184:187], v[196:199], v[34:37]
	s_waitcnt lgkmcnt(0)
	v_mfma_f32_16x16x32_bf16 v[2:5], v[216:219], v[232:235], v[2:5]
	v_mfma_f32_16x16x32_bf16 v[10:13], v[204:207], v[220:223], v[10:13]
	v_mfma_f32_16x16x32_bf16 v[22:25], v[204:207], v[224:227], v[22:25]
	v_mfma_f32_16x16x32_bf16 v[30:33], v[204:207], v[228:231], v[30:33]
	v_mfma_f32_16x16x32_bf16 v[38:41], v[204:207], v[232:235], v[38:41]
	v_mfma_f32_16x16x32_bf16 v[46:49], v[208:211], v[220:223], v[46:49]
	v_mfma_f32_16x16x32_bf16 v[62:65], v[208:211], v[224:227], v[62:65]
	v_mfma_f32_16x16x32_bf16 v[70:73], v[208:211], v[228:231], v[70:73]
	v_mfma_f32_16x16x32_bf16 v[54:57], v[208:211], v[232:235], v[54:57]
	v_mfma_f32_16x16x32_bf16 v[58:61], v[212:215], v[220:223], v[58:61]
	v_mfma_f32_16x16x32_bf16 v[78:81], v[212:215], v[224:227], v[78:81]
	v_mfma_f32_16x16x32_bf16 v[74:77], v[212:215], v[228:231], v[74:77]
	v_mfma_f32_16x16x32_bf16 v[14:17], v[212:215], v[232:235], v[14:17]
	v_mfma_f32_16x16x32_bf16 v[18:21], v[216:219], v[220:223], v[18:21]
	v_mfma_f32_16x16x32_bf16 v[42:45], v[216:219], v[224:227], v[42:45]
	v_mfma_f32_16x16x32_bf16 v[34:37], v[216:219], v[228:231], v[34:37]
	s_setprio 0
	s_mov_b32 m0, s13
	v_lshl_add_u64 v[148:149], v[6:7], 0, s[2:3]
	s_waitcnt vmcnt(0)
	s_barrier
	global_load_lds_dwordx4 v[148:149], off
	v_lshl_add_u64 v[148:149], v[8:9], 0, s[2:3]
	s_mov_b32 m0, s12
	s_mov_b64 s[0:1], 0x8280
	global_load_lds_dwordx4 v[148:149], off
	v_lshl_add_u64 v[148:149], v[6:7], 0, s[0:1]
	s_mov_b32 m0, s21
	s_mov_b64 s[0:1], 0x10280
	global_load_lds_dwordx4 v[148:149], off
	v_lshl_add_u64 v[148:149], v[26:27], 0, s[2:3]
	s_mov_b32 m0, s5
	s_nop 0
	global_load_lds_dwordx4 v[148:149], off
	v_lshl_add_u64 v[148:149], v[6:7], 0, s[0:1]
	s_mov_b32 m0, s8
	s_mov_b64 s[0:1], 0x18280
	global_load_lds_dwordx4 v[148:149], off
	v_lshl_add_u64 v[148:149], v[28:29], 0, s[2:3]
	s_mov_b32 m0, s9
	s_nop 0
	global_load_lds_dwordx4 v[148:149], off
	v_lshl_add_u64 v[148:149], v[6:7], 0, s[0:1]
	s_mov_b32 m0, s10
	s_nop 0
	global_load_lds_dwordx4 v[148:149], off
	v_lshl_add_u64 v[148:149], v[50:51], 0, s[2:3]
	s_mov_b32 m0, s11
	s_nop 0
	global_load_lds_dwordx4 v[148:149], off
	ds_read_b128 v[148:151], v0
	ds_read_b128 v[152:155], v0 offset:2048
	ds_read_b128 v[180:183], v0 offset:4096
	ds_read_b128 v[184:187], v0 offset:6144
	ds_read_b128 v[188:191], v145 offset:16384
	ds_read_b128 v[192:195], v145 offset:18432
	ds_read_b128 v[196:199], v145 offset:20480
	ds_read_b128 v[200:203], v145 offset:22528
	ds_read_b128 v[204:207], v146
	ds_read_b128 v[208:211], v146 offset:2048
	ds_read_b128 v[212:215], v146 offset:4096
	ds_read_b128 v[216:219], v146 offset:6144
	ds_read_b128 v[220:223], v147 offset:16384
	ds_read_b128 v[224:227], v147 offset:18432
	ds_read_b128 v[228:231], v147 offset:20480
	ds_read_b128 v[232:235], v147 offset:22528
	s_setprio 1
	s_waitcnt lgkmcnt(8)
	v_mfma_f32_16x16x32_bf16 v[2:5], v[184:187], v[200:203], v[2:5]
	v_mfma_f32_16x16x32_bf16 v[10:13], v[148:151], v[188:191], v[10:13]
	v_mfma_f32_16x16x32_bf16 v[22:25], v[148:151], v[192:195], v[22:25]
	v_mfma_f32_16x16x32_bf16 v[30:33], v[148:151], v[196:199], v[30:33]
	v_mfma_f32_16x16x32_bf16 v[38:41], v[148:151], v[200:203], v[38:41]
	v_mfma_f32_16x16x32_bf16 v[46:49], v[152:155], v[188:191], v[46:49]
	v_mfma_f32_16x16x32_bf16 v[62:65], v[152:155], v[192:195], v[62:65]
	v_mfma_f32_16x16x32_bf16 v[70:73], v[152:155], v[196:199], v[70:73]
	v_mfma_f32_16x16x32_bf16 v[54:57], v[152:155], v[200:203], v[54:57]
	v_mfma_f32_16x16x32_bf16 v[58:61], v[180:183], v[188:191], v[58:61]
	v_mfma_f32_16x16x32_bf16 v[78:81], v[180:183], v[192:195], v[78:81]
	v_mfma_f32_16x16x32_bf16 v[74:77], v[180:183], v[196:199], v[74:77]
	v_mfma_f32_16x16x32_bf16 v[14:17], v[180:183], v[200:203], v[14:17]
	v_mfma_f32_16x16x32_bf16 v[18:21], v[184:187], v[188:191], v[18:21]
	v_mfma_f32_16x16x32_bf16 v[42:45], v[184:187], v[192:195], v[42:45]
	v_mfma_f32_16x16x32_bf16 v[34:37], v[184:187], v[196:199], v[34:37]
	s_waitcnt lgkmcnt(0)
	v_mfma_f32_16x16x32_bf16 v[2:5], v[216:219], v[232:235], v[2:5]
	v_mfma_f32_16x16x32_bf16 v[10:13], v[204:207], v[220:223], v[10:13]
	v_mfma_f32_16x16x32_bf16 v[22:25], v[204:207], v[224:227], v[22:25]
	v_mfma_f32_16x16x32_bf16 v[30:33], v[204:207], v[228:231], v[30:33]
	v_mfma_f32_16x16x32_bf16 v[38:41], v[204:207], v[232:235], v[38:41]
	v_mfma_f32_16x16x32_bf16 v[46:49], v[208:211], v[220:223], v[46:49]
	v_mfma_f32_16x16x32_bf16 v[62:65], v[208:211], v[224:227], v[62:65]
	v_mfma_f32_16x16x32_bf16 v[70:73], v[208:211], v[228:231], v[70:73]
	v_mfma_f32_16x16x32_bf16 v[54:57], v[208:211], v[232:235], v[54:57]
	v_mfma_f32_16x16x32_bf16 v[58:61], v[212:215], v[220:223], v[58:61]
	v_mfma_f32_16x16x32_bf16 v[78:81], v[212:215], v[224:227], v[78:81]
	v_mfma_f32_16x16x32_bf16 v[74:77], v[212:215], v[228:231], v[74:77]
	v_mfma_f32_16x16x32_bf16 v[14:17], v[212:215], v[232:235], v[14:17]
	v_mfma_f32_16x16x32_bf16 v[18:21], v[216:219], v[220:223], v[18:21]
	v_mfma_f32_16x16x32_bf16 v[42:45], v[216:219], v[224:227], v[42:45]
	v_mfma_f32_16x16x32_bf16 v[34:37], v[216:219], v[228:231], v[34:37]
	s_setprio 0
	s_mov_b32 m0, s25
	v_lshl_add_u64 v[148:149], v[6:7], 0, s[14:15]
	s_waitcnt vmcnt(0)
	s_barrier
; #define MFMA16(a, b, c) __builtin_amdgcn_mfma_f32_16x16x32_bf16((a), (b), (c), 0, 0, 0)
; DI void gemm_tile(const bf16_t* __restrict__ A, int lda, const bf16_t* __restrict__ Bt, int ldb, int bvalid, int K, f32x4 (&acc)[4][4], char* lds, bool preloaded = false) {
;     ...
;   auto compute = [&](int st) {
;     const char* base = lds + st * 32768;
;     bf16x8 af[2][4], bfr[2][4];
; #pragma unroll
;     for (int s = 0; s < 2; ++s) {
;       const int ch = ((4 * s + fq) ^ fx) << 4;
; #pragma unroll
;       for (int mi = 0; mi < 4; ++mi) af[s][mi] = *(const bf16x8*)(base + (wm * 64 + mi * 16 + fr) * 128 + ch);
; #pragma unroll
;       for (int ni = 0; ni < 4; ++ni) bfr[s][ni] = *(const bf16x8*)(base + 16384 + (wn * 64 + ni * 16 + fr) * 128 + ch);
;     }
;     __builtin_amdgcn_s_setprio(1);
; #pragma unroll
;     for (int s = 0; s < 2; ++s)
; #pragma unroll
;       for (int mi = 0; mi < 4; ++mi)
; #pragma unroll
;         for (int ni = 0; ni < 4; ++ni) acc[mi][ni] = MFMA16(af[s][mi], bfr[s][ni], acc[mi][ni]);
;     __builtin_amdgcn_s_setprio(0);
;   };
;   const int nk = K >> 6;
;   if (!preloaded) { GLDS(0, 0) }
;   __syncthreads();
;   for (int kt = 0; kt < nk; ++kt) {
;     if (kt + 1 < nk) { GLDS((kt + 1) & 1, (kt + 1) << 6) }
;     compute(kt & 1);
;     __syncthreads();
;   }
	global_load_lds_dwordx4 v[148:149], off
	v_lshl_add_u64 v[148:149], v[8:9], 0, s[14:15]
	s_mov_b32 m0, s22
	s_mov_b64 s[0:1], 0x8300
	global_load_lds_dwordx4 v[148:149], off
	v_lshl_add_u64 v[148:149], v[6:7], 0, s[0:1]
	s_mov_b32 m0, s23
	s_mov_b64 s[0:1], 0x10300
	global_load_lds_dwordx4 v[148:149], off
	v_lshl_add_u64 v[148:149], v[26:27], 0, s[14:15]
	s_mov_b32 m0, s24
	s_nop 0
	global_load_lds_dwordx4 v[148:149], off
	v_lshl_add_u64 v[148:149], v[6:7], 0, s[0:1]
	s_mov_b32 m0, s26
	s_mov_b64 s[0:1], 0x18300
	global_load_lds_dwordx4 v[148:149], off
	v_lshl_add_u64 v[148:149], v[28:29], 0, s[14:15]
	s_mov_b32 m0, s27
	s_nop 0
	global_load_lds_dwordx4 v[148:149], off
	v_lshl_add_u64 v[148:149], v[6:7], 0, s[0:1]
	s_mov_b32 m0, s28
	s_nop 0
	global_load_lds_dwordx4 v[148:149], off
	v_lshl_add_u64 v[148:149], v[50:51], 0, s[14:15]
	s_mov_b32 m0, s29
	s_nop 0
	global_load_lds_dwordx4 v[148:149], off
	ds_read_b128 v[148:151], v0 offset:32768
	ds_read_b128 v[152:155], v0 offset:34816
	ds_read_b128 v[180:183], v0 offset:36864
	ds_read_b128 v[184:187], v0 offset:38912
	ds_read_b128 v[188:191], v145 offset:49152
	ds_read_b128 v[192:195], v145 offset:51200
	ds_read_b128 v[196:199], v145 offset:53248
	ds_read_b128 v[200:203], v145 offset:55296
	ds_read_b128 v[204:207], v146 offset:32768
	ds_read_b128 v[208:211], v146 offset:34816
	ds_read_b128 v[212:215], v146 offset:36864
	ds_read_b128 v[216:219], v146 offset:38912
	ds_read_b128 v[220:223], v147 offset:49152
	ds_read_b128 v[224:227], v147 offset:51200
	ds_read_b128 v[228:231], v147 offset:53248
	ds_read_b128 v[232:235], v147 offset:55296
	s_setprio 1
	s_waitcnt lgkmcnt(8)
	v_mfma_f32_16x16x32_bf16 v[2:5], v[184:187], v[200:203], v[2:5]
	v_mfma_f32_16x16x32_bf16 v[10:13], v[148:151], v[188:191], v[10:13]
	v_mfma_f32_16x16x32_bf16 v[22:25], v[148:151], v[192:195], v[22:25]
	v_mfma_f32_16x16x32_bf16 v[30:33], v[148:151], v[196:199], v[30:33]
	v_mfma_f32_16x16x32_bf16 v[38:41], v[148:151], v[200:203], v[38:41]
	v_mfma_f32_16x16x32_bf16 v[46:49], v[152:155], v[188:191], v[46:49]
	v_mfma_f32_16x16x32_bf16 v[62:65], v[152:155], v[192:195], v[62:65]
	v_mfma_f32_16x16x32_bf16 v[70:73], v[152:155], v[196:199], v[70:73]
	v_mfma_f32_16x16x32_bf16 v[54:57], v[152:155], v[200:203], v[54:57]
	v_mfma_f32_16x16x32_bf16 v[58:61], v[180:183], v[188:191], v[58:61]
	v_mfma_f32_16x16x32_bf16 v[78:81], v[180:183], v[192:195], v[78:81]
	v_mfma_f32_16x16x32_bf16 v[74:77], v[180:183], v[196:199], v[74:77]
	v_mfma_f32_16x16x32_bf16 v[14:17], v[180:183], v[200:203], v[14:17]
	v_mfma_f32_16x16x32_bf16 v[18:21], v[184:187], v[188:191], v[18:21]
	v_mfma_f32_16x16x32_bf16 v[42:45], v[184:187], v[192:195], v[42:45]
	v_mfma_f32_16x16x32_bf16 v[34:37], v[184:187], v[196:199], v[34:37]
	s_waitcnt lgkmcnt(0)
	v_mfma_f32_16x16x32_bf16 v[2:5], v[216:219], v[232:235], v[2:5]
	v_mfma_f32_16x16x32_bf16 v[10:13], v[204:207], v[220:223], v[10:13]
	v_mfma_f32_16x16x32_bf16 v[22:25], v[204:207], v[224:227], v[22:25]
	v_mfma_f32_16x16x32_bf16 v[30:33], v[204:207], v[228:231], v[30:33]
	v_mfma_f32_16x16x32_bf16 v[38:41], v[204:207], v[232:235], v[38:41]
	v_mfma_f32_16x16x32_bf16 v[46:49], v[208:211], v[220:223], v[46:49]
	v_mfma_f32_16x16x32_bf16 v[62:65], v[208:211], v[224:227], v[62:65]
	v_mfma_f32_16x16x32_bf16 v[70:73], v[208:211], v[228:231], v[70:73]
	v_mfma_f32_16x16x32_bf16 v[54:57], v[208:211], v[232:235], v[54:57]
	v_mfma_f32_16x16x32_bf16 v[58:61], v[212:215], v[220:223], v[58:61]
	v_mfma_f32_16x16x32_bf16 v[78:81], v[212:215], v[224:227], v[78:81]
	v_mfma_f32_16x16x32_bf16 v[74:77], v[212:215], v[228:231], v[74:77]
	v_mfma_f32_16x16x32_bf16 v[14:17], v[212:215], v[232:235], v[14:17]
	v_mfma_f32_16x16x32_bf16 v[18:21], v[216:219], v[220:223], v[18:21]
	v_mfma_f32_16x16x32_bf16 v[42:45], v[216:219], v[224:227], v[42:45]
	v_mfma_f32_16x16x32_bf16 v[34:37], v[216:219], v[228:231], v[34:37]
	s_setprio 0
	v_readfirstlane_b32 s12, v143
	v_lshl_add_u64 v[148:149], v[6:7], 0, s[64:65]
	s_mov_b32 m0, s12
	v_readfirstlane_b32 s12, v142
	s_waitcnt vmcnt(0)
	s_barrier
	global_load_lds_dwordx4 v[148:149], off
	v_lshl_add_u64 v[8:9], v[8:9], 0, s[64:65]
	s_mov_b32 m0, s12
	s_mov_b64 s[0:1], 0x8380
	v_readfirstlane_b32 s12, v144
	global_load_lds_dwordx4 v[8:9], off
	v_lshl_add_u64 v[8:9], v[6:7], 0, s[0:1]
	s_mov_b32 m0, s12
	s_mov_b64 s[0:1], 0x10380
	global_load_lds_dwordx4 v[8:9], off
	v_lshl_add_u64 v[8:9], v[26:27], 0, s[64:65]
	s_mov_b32 m0, s5
	s_nop 0
	global_load_lds_dwordx4 v[8:9], off
	v_lshl_add_u64 v[8:9], v[6:7], 0, s[0:1]
	s_mov_b32 m0, s8
	s_mov_b64 s[0:1], 0x18380
	global_load_lds_dwordx4 v[8:9], off
	v_lshl_add_u64 v[8:9], v[28:29], 0, s[64:65]
	s_mov_b32 m0, s9
	v_lshl_add_u64 v[6:7], v[6:7], 0, s[0:1]
	global_load_lds_dwordx4 v[8:9], off
	s_mov_b32 m0, s10
	s_nop 0
	global_load_lds_dwordx4 v[6:7], off
	v_lshl_add_u64 v[6:7], v[50:51], 0, s[64:65]
	s_mov_b32 m0, s11
	s_nop 0
	global_load_lds_dwordx4 v[6:7], off
	ds_read_b128 v[6:9], v0
	ds_read_b128 v[26:29], v0 offset:2048
	ds_read_b128 v[148:151], v0 offset:4096
	ds_read_b128 v[152:155], v0 offset:6144
	ds_read_b128 v[180:183], v145 offset:16384
	ds_read_b128 v[184:187], v145 offset:18432
	ds_read_b128 v[188:191], v145 offset:20480
	ds_read_b128 v[192:195], v145 offset:22528
	ds_read_b128 v[196:199], v146
	ds_read_b128 v[200:203], v146 offset:2048
	ds_read_b128 v[204:207], v146 offset:4096
	ds_read_b128 v[208:211], v146 offset:6144
	ds_read_b128 v[212:215], v147 offset:16384
	ds_read_b128 v[216:219], v147 offset:18432
	ds_read_b128 v[220:223], v147 offset:20480
	ds_read_b128 v[224:227], v147 offset:22528
	s_setprio 1
	s_waitcnt lgkmcnt(8)
; DI void gemm_tile(const bf16_t* __restrict__ A, int lda, const bf16_t* __restrict__ Bt, int ldb, int bvalid, int K, f32x4 (&acc)[4][4], char* lds, bool preloaded = false) {
;     ...
;   for (int kt = 0; kt < nk; ++kt) {
;     if (kt + 1 < nk) { GLDS((kt + 1) & 1, (kt + 1) << 6) }
;     compute(kt & 1);
;     __syncthreads();
;   }
; DI void phaseD_tile(const P& p, int layer, int mt, int nt, char* lds) {
;     ...
; #pragma unroll
;   for (int mi = 0; mi < 4; ++mi)
; #pragma unroll
;     for (int ni = 0; ni < 4; ++ni)
; #pragma unroll
;       for (int j = 0; j < 4; ++j) acc[mi][ni][j] *= fmaxf((float)((gav[mi][ni] >> (8 * j)) & 255u), 1.f) * (1.f / 255.f);
	v_mfma_f32_16x16x32_bf16 v[2:5], v[152:155], v[192:195], v[2:5]
	v_mfma_f32_16x16x32_bf16 v[10:13], v[6:9], v[180:183], v[10:13]
	v_mfma_f32_16x16x32_bf16 v[22:25], v[6:9], v[184:187], v[22:25]
	v_mfma_f32_16x16x32_bf16 v[30:33], v[6:9], v[188:191], v[30:33]
	v_mfma_f32_16x16x32_bf16 v[6:9], v[6:9], v[192:195], v[38:41]
	v_mfma_f32_16x16x32_bf16 v[38:41], v[26:29], v[180:183], v[46:49]
	v_mfma_f32_16x16x32_bf16 v[46:49], v[26:29], v[184:187], v[62:65]
	v_mfma_f32_16x16x32_bf16 v[62:65], v[26:29], v[188:191], v[70:73]
	v_mfma_f32_16x16x32_bf16 v[26:29], v[26:29], v[192:195], v[54:57]
	v_mfma_f32_16x16x32_bf16 v[54:57], v[148:151], v[180:183], v[58:61]
	v_mfma_f32_16x16x32_bf16 v[58:61], v[148:151], v[184:187], v[78:81]
	v_mfma_f32_16x16x32_bf16 v[70:73], v[148:151], v[188:191], v[74:77]
	v_mfma_f32_16x16x32_bf16 v[14:17], v[148:151], v[192:195], v[14:17]
	v_mfma_f32_16x16x32_bf16 v[18:21], v[152:155], v[180:183], v[18:21]
	v_mfma_f32_16x16x32_bf16 v[42:45], v[152:155], v[184:187], v[42:45]
	v_mfma_f32_16x16x32_bf16 v[34:37], v[152:155], v[188:191], v[34:37]
	s_waitcnt lgkmcnt(0)
	v_mfma_f32_16x16x32_bf16 v[2:5], v[208:211], v[224:227], v[2:5]
	v_mfma_f32_16x16x32_bf16 v[10:13], v[196:199], v[212:215], v[10:13]
	v_mfma_f32_16x16x32_bf16 v[22:25], v[196:199], v[216:219], v[22:25]
	v_mfma_f32_16x16x32_bf16 v[30:33], v[196:199], v[220:223], v[30:33]
	v_mfma_f32_16x16x32_bf16 v[6:9], v[196:199], v[224:227], v[6:9]
	v_mfma_f32_16x16x32_bf16 v[38:41], v[200:203], v[212:215], v[38:41]
	v_mfma_f32_16x16x32_bf16 v[46:49], v[200:203], v[216:219], v[46:49]
	v_mfma_f32_16x16x32_bf16 v[62:65], v[200:203], v[220:223], v[62:65]
	v_mfma_f32_16x16x32_bf16 v[26:29], v[200:203], v[224:227], v[26:29]
	v_mfma_f32_16x16x32_bf16 v[54:57], v[204:207], v[212:215], v[54:57]
	v_mfma_f32_16x16x32_bf16 v[58:61], v[204:207], v[216:219], v[58:61]
	v_mfma_f32_16x16x32_bf16 v[70:73], v[204:207], v[220:223], v[70:73]
	v_mfma_f32_16x16x32_bf16 v[14:17], v[204:207], v[224:227], v[14:17]
	v_mfma_f32_16x16x32_bf16 v[18:21], v[208:211], v[212:215], v[18:21]
	v_mfma_f32_16x16x32_bf16 v[42:45], v[208:211], v[216:219], v[42:45]
	v_mfma_f32_16x16x32_bf16 v[34:37], v[208:211], v[220:223], v[34:37]
	s_setprio 0
	s_waitcnt vmcnt(0)
	s_barrier
	ds_read_b128 v[74:77], v0 offset:32768
	ds_read_b128 v[78:81], v0 offset:34816
	ds_read_b128 v[148:151], v0 offset:36864
	ds_read_b128 v[152:155], v0 offset:38912
	ds_read_b128 v[180:183], v145 offset:49152
	ds_read_b128 v[184:187], v145 offset:51200
	ds_read_b128 v[188:191], v145 offset:53248
	ds_read_b128 v[142:145], v145 offset:55296
	ds_read_b128 v[192:195], v146 offset:32768
	ds_read_b128 v[196:199], v146 offset:34816
	ds_read_b128 v[200:203], v146 offset:36864
	ds_read_b128 v[204:207], v146 offset:38912
	ds_read_b128 v[208:211], v147 offset:49152
	ds_read_b128 v[212:215], v147 offset:51200
	ds_read_b128 v[216:219], v147 offset:53248
	ds_read_b128 v[220:223], v147 offset:55296
	s_setprio 1
	s_waitcnt lgkmcnt(8)
	v_mfma_f32_16x16x32_bf16 v[2:5], v[152:155], v[142:145], v[2:5]
	v_mfma_f32_16x16x32_bf16 v[10:13], v[74:77], v[180:183], v[10:13]
	v_mfma_f32_16x16x32_bf16 v[22:25], v[74:77], v[184:187], v[22:25]
	v_mfma_f32_16x16x32_bf16 v[30:33], v[74:77], v[188:191], v[30:33]
	v_mfma_f32_16x16x32_bf16 v[6:9], v[74:77], v[142:145], v[6:9]
	v_mfma_f32_16x16x32_bf16 v[38:41], v[78:81], v[180:183], v[38:41]
	v_mfma_f32_16x16x32_bf16 v[46:49], v[78:81], v[184:187], v[46:49]
	v_mfma_f32_16x16x32_bf16 v[62:65], v[78:81], v[188:191], v[62:65]
	v_mfma_f32_16x16x32_bf16 v[26:29], v[78:81], v[142:145], v[26:29]
	v_mfma_f32_16x16x32_bf16 v[54:57], v[148:151], v[180:183], v[54:57]
	v_mfma_f32_16x16x32_bf16 v[58:61], v[148:151], v[184:187], v[58:61]
	v_mfma_f32_16x16x32_bf16 v[70:73], v[148:151], v[188:191], v[70:73]
	v_mfma_f32_16x16x32_bf16 v[14:17], v[148:151], v[142:145], v[14:17]
	v_mfma_f32_16x16x32_bf16 v[18:21], v[152:155], v[180:183], v[18:21]
	v_mfma_f32_16x16x32_bf16 v[42:45], v[152:155], v[184:187], v[42:45]
	v_mfma_f32_16x16x32_bf16 v[34:37], v[152:155], v[188:191], v[34:37]
	s_waitcnt lgkmcnt(0)
	v_mfma_f32_16x16x32_bf16 v[2:5], v[204:207], v[220:223], v[2:5]
	v_mfma_f32_16x16x32_bf16 v[10:13], v[192:195], v[208:211], v[10:13]
	v_mfma_f32_16x16x32_bf16 v[22:25], v[192:195], v[212:215], v[22:25]
	v_mfma_f32_16x16x32_bf16 v[30:33], v[192:195], v[216:219], v[30:33]
	v_mfma_f32_16x16x32_bf16 v[6:9], v[192:195], v[220:223], v[6:9]
	v_mfma_f32_16x16x32_bf16 v[38:41], v[196:199], v[208:211], v[38:41]
	v_mfma_f32_16x16x32_bf16 v[46:49], v[196:199], v[212:215], v[46:49]
	v_mfma_f32_16x16x32_bf16 v[62:65], v[196:199], v[216:219], v[62:65]
	v_mfma_f32_16x16x32_bf16 v[26:29], v[196:199], v[220:223], v[26:29]
	v_mfma_f32_16x16x32_bf16 v[54:57], v[200:203], v[208:211], v[54:57]
	v_mfma_f32_16x16x32_bf16 v[58:61], v[200:203], v[212:215], v[58:61]
	v_mfma_f32_16x16x32_bf16 v[70:73], v[200:203], v[216:219], v[70:73]
	v_mfma_f32_16x16x32_bf16 v[14:17], v[200:203], v[220:223], v[14:17]
	v_mfma_f32_16x16x32_bf16 v[18:21], v[204:207], v[208:211], v[18:21]
	v_mfma_f32_16x16x32_bf16 v[42:45], v[204:207], v[212:215], v[42:45]
	v_mfma_f32_16x16x32_bf16 v[34:37], v[204:207], v[216:219], v[34:37]
	s_setprio 0
	v_mul_f32_e32 v0, 0x3b808081, v100
	v_mul_f32_e32 v10, v0, v10
	v_mul_f32_e32 v0, 0x3b808081, v101
	v_mul_f32_e32 v11, v0, v11
	v_mul_f32_e32 v0, 0x3b808081, v102
	v_mul_f32_e32 v12, v0, v12
	v_mul_f32_e32 v0, 0x3b808081, v103
	v_mul_f32_e32 v13, v0, v13
	v_mul_f32_e32 v0, 0x3b808081, v104
	v_mul_f32_e32 v22, v0, v22
	v_mul_f32_e32 v0, 0x3b808081, v105
	v_mul_f32_e32 v23, v0, v23
	v_mul_f32_e32 v0, 0x3b808081, v106
	v_mul_f32_e32 v24, v0, v24
; DI unsigned pk2(float lo, float hi) { unsigned r; asm("v_cvt_pk_bf16_f32 %0, %1, %2" : "=v"(r) : "v"(lo), "v"(hi)); return r; }
; DI void phaseD_tile(const P& p, int layer, int mt, int nt, char* lds) {
;     ...
;   for (int mi = 0; mi < 4; ++mi)
; #pragma unroll
;     for (int ni = 0; ni < 4; ++ni)
; #pragma unroll
;       for (int j = 0; j < 4; ++j) acc[mi][ni][j] *= fmaxf((float)((gav[mi][ni] >> (8 * j)) & 255u), 1.f) * (1.f / 255.f);
;   float* tile = (float*)lds;
;   stage_acc(acc, tile, wm, wn, fr, fq);
;   __syncthreads();
;   bf16_t* MG = (bf16_t*)(p.ws + W_MERGED);
; #pragma unroll 1
;   for (int ps = 0; ps < 16; ++ps) {
;     const int lr = ps * 8 + wm * 4 + fq;
;     const f32x4 v = *(const f32x4*)(tile + lr * EPS + wn * 64 + fr * 4);
;     *(u32x2*)(MG + (size_t)(row0 + lr) * LDX + col0 + wn * 64 + fr * 4) = u32x2{pk2(v.x, v.y), pk2(v.z, v.w)};
	v_mul_f32_e32 v0, 0x3b808081, v107
	v_mul_f32_e32 v25, v0, v25
	v_mul_f32_e32 v0, 0x3b808081, v108
	v_mul_f32_e32 v30, v0, v30
	v_mul_f32_e32 v0, 0x3b808081, v109
	v_mul_f32_e32 v31, v0, v31
	v_mul_f32_e32 v0, 0x3b808081, v110
	v_mul_f32_e32 v32, v0, v32
	v_mul_f32_e32 v0, 0x3b808081, v111
	v_mul_f32_e32 v33, v0, v33
	v_mul_f32_e32 v0, 0x3b808081, v112
	v_mul_f32_e32 v6, v0, v6
	v_mul_f32_e32 v0, 0x3b808081, v113
	v_mul_f32_e32 v7, v0, v7
	v_mul_f32_e32 v0, 0x3b808081, v114
	v_mul_f32_e32 v8, v0, v8
	v_mul_f32_e32 v0, 0x3b808081, v115
	v_mul_f32_e32 v9, v0, v9
	v_mul_f32_e32 v0, 0x3b808081, v94
	v_mul_f32_e32 v38, v0, v38
	v_mul_f32_e32 v0, 0x3b808081, v95
	v_mul_f32_e32 v39, v0, v39
	v_mul_f32_e32 v0, 0x3b808081, v96
	v_mul_f32_e32 v40, v0, v40
	v_mul_f32_e32 v0, 0x3b808081, v97
	v_mul_f32_e32 v41, v0, v41
	v_mul_f32_e32 v0, 0x3b808081, v90
	v_mul_f32_e32 v46, v0, v46
	v_mul_f32_e32 v0, 0x3b808081, v91
	v_mul_f32_e32 v47, v0, v47
	v_mul_f32_e32 v0, 0x3b808081, v92
	v_mul_f32_e32 v48, v0, v48
	v_mul_f32_e32 v0, 0x3b808081, v93
	v_mul_f32_e32 v49, v0, v49
	v_mul_f32_e32 v0, 0x3b808081, v116
	v_mul_f32_e32 v50, v0, v62
	v_mul_f32_e32 v0, 0x3b808081, v117
	v_mul_f32_e32 v51, v0, v63
	v_mul_f32_e32 v0, 0x3b808081, v118
	v_mul_f32_e32 v62, v0, v64
	v_mul_f32_e32 v0, 0x3b808081, v119
	v_mul_f32_e32 v63, v0, v65
	v_mul_f32_e32 v0, 0x3b808081, v120
	v_mul_f32_e32 v26, v0, v26
	v_mul_f32_e32 v0, 0x3b808081, v121
	v_mul_f32_e32 v27, v0, v27
	v_mul_f32_e32 v0, 0x3b808081, v122
	v_mul_f32_e32 v28, v0, v28
	v_mul_f32_e32 v0, 0x3b808081, v123
	v_mul_f32_e32 v29, v0, v29
	v_mul_f32_e32 v0, 0x3b808081, v86
	v_mul_f32_e32 v54, v0, v54
	v_mul_f32_e32 v0, 0x3b808081, v87
	v_mul_f32_e32 v55, v0, v55
	v_mul_f32_e32 v0, 0x3b808081, v88
	v_mul_f32_e32 v56, v0, v56
	v_mul_f32_e32 v0, 0x3b808081, v89
	v_mul_f32_e32 v57, v0, v57
	v_mul_f32_e32 v0, 0x3b808081, v82
	v_mul_f32_e32 v58, v0, v58
	v_mul_f32_e32 v0, 0x3b808081, v83
	v_mul_f32_e32 v59, v0, v59
	v_mul_f32_e32 v0, 0x3b808081, v84
	v_mul_f32_e32 v60, v0, v60
	v_mul_f32_e32 v0, 0x3b808081, v85
	v_mul_f32_e32 v61, v0, v61
	v_mul_f32_e32 v0, 0x3b808081, v124
	v_mul_f32_e32 v64, v0, v70
	v_mul_f32_e32 v0, 0x3b808081, v125
	v_mul_f32_e32 v65, v0, v71
	v_mul_f32_e32 v0, 0x3b808081, v126
	v_mul_f32_e32 v70, v0, v72
	v_mul_f32_e32 v0, 0x3b808081, v127
	v_mul_f32_e32 v71, v0, v73
	v_mul_f32_e32 v0, 0x3b808081, v128
	v_mul_f32_e32 v14, v0, v14
	v_mul_f32_e32 v0, 0x3b808081, v129
	v_mul_f32_e32 v15, v0, v15
	v_mul_f32_e32 v0, 0x3b808081, v130
	v_mul_f32_e32 v16, v0, v16
	v_mul_f32_e32 v0, 0x3b808081, v131
	v_mul_f32_e32 v17, v0, v17
	v_mul_f32_e32 v0, 0x3b808081, v66
	v_mul_f32_e32 v18, v0, v18
	v_mul_f32_e32 v0, 0x3b808081, v67
	v_mul_f32_e32 v19, v0, v19
	v_mul_f32_e32 v0, 0x3b808081, v68
	v_mul_f32_e32 v20, v0, v20
	v_mul_f32_e32 v0, 0x3b808081, v69
	v_mul_f32_e32 v21, v0, v21
	v_mul_f32_e32 v0, 0x3b808081, v52
	v_mul_f32_e32 v42, v0, v42
	v_mul_f32_e32 v0, 0x3b808081, v53
	v_mul_f32_e32 v43, v0, v43
	v_mul_f32_e32 v0, 0x3b808081, v132
	v_mul_f32_e32 v44, v0, v44
	v_mul_f32_e32 v0, 0x3b808081, v133
	v_mul_f32_e32 v45, v0, v45
	v_mul_f32_e32 v0, 0x3b808081, v134
	v_mul_f32_e32 v34, v0, v34
	v_mul_f32_e32 v0, 0x3b808081, v135
	v_mul_f32_e32 v35, v0, v35
	v_mul_f32_e32 v0, 0x3b808081, v136
	v_mul_f32_e32 v36, v0, v36
	v_mul_f32_e32 v0, 0x3b808081, v137
	v_mul_f32_e32 v37, v0, v37
	v_mul_f32_e32 v0, 0x3b808081, v138
	v_mul_f32_e32 v52, v0, v2
	v_mul_f32_e32 v0, 0x3b808081, v139
	v_mul_f32_e32 v53, v0, v3
	v_mul_f32_e32 v0, 0x3b808081, v140
	v_mul_f32_e32 v4, v0, v4
	v_mul_f32_e32 v0, 0x3b808081, v141
	v_bfe_u32 v66, v99, 4, 2
	v_mul_f32_e32 v5, v0, v5
	v_lshlrev_b32_e32 v0, 2, v66
	s_lshl_b32 s5, s20, 8
	v_lshl_or_b32 v2, s19, 6, v0
	v_lshl_or_b32 v0, v98, 2, s5
	v_mad_u64_u32 v[2:3], s[8:9], v2, s56, v[0:1]
	v_add_u32_e32 v0, 0x400, v2
	s_lshl_b32 s8, s19, 2
	s_lshl_b64 s[6:7], s[6:7], 1
	s_mov_b64 s[58:59], s[60:61]
	s_barrier
	ds_write2_b32 v2, v10, v22 offset1:16
	ds_write2_b32 v2, v11, v23 offset0:132 offset1:148
	ds_write2_b32 v0, v12, v24 offset0:8 offset1:24
	ds_write2_b32 v0, v13, v25 offset0:140 offset1:156
	ds_write2_b32 v2, v30, v6 offset0:32 offset1:48
	ds_write2_b32 v2, v31, v7 offset0:164 offset1:180
	ds_write2_b32 v0, v32, v8 offset0:40 offset1:56
	ds_write2_b32 v0, v33, v9 offset0:172 offset1:188
	v_add_u32_e32 v0, 0x2000, v2
	v_add_u32_e32 v3, 0x2400, v2
	s_add_u32 s6, s58, s6
	ds_write2_b32 v0, v38, v46 offset0:64 offset1:80
	ds_write2_b32 v0, v39, v47 offset0:196 offset1:212
	ds_write2_b32 v3, v40, v48 offset0:72 offset1:88
	ds_write2_b32 v3, v41, v49 offset0:204 offset1:220
	ds_write2_b32 v0, v50, v26 offset0:96 offset1:112
	ds_write2_b32 v0, v51, v27 offset0:228 offset1:244
	ds_write2_b32 v3, v62, v28 offset0:104 offset1:120
	ds_write2_b32 v3, v63, v29 offset0:236 offset1:252
	v_add_u32_e32 v0, 0x4000, v2
	v_add_u32_e32 v3, 0x4400, v2
	v_add_u32_e32 v6, 0x4800, v2
	s_addc_u32 s7, s59, s7
	s_lshl_b32 s9, s20, 7
	ds_write2_b32 v0, v54, v58 offset0:128 offset1:144
	ds_write2_b32 v3, v55, v59 offset0:4 offset1:20
	ds_write2_b32 v3, v56, v60 offset0:136 offset1:152
	ds_write2_b32 v6, v57, v61 offset0:12 offset1:28
	ds_write2_b32 v0, v64, v14 offset0:160 offset1:176
	ds_write2_b32 v3, v65, v15 offset0:36 offset1:52
	ds_write2_b32 v3, v70, v16 offset0:168 offset1:184
	ds_write2_b32 v6, v71, v17 offset0:44 offset1:60
	v_add_u32_e32 v0, 0x6000, v2
	v_add_u32_e32 v3, 0x6400, v2
	v_add_u32_e32 v2, 0x6800, v2
	s_add_u32 s6, s6, s9
	s_mulk_i32 s19, 0x840
	ds_write2_b32 v0, v18, v42 offset0:192 offset1:208
	ds_write2_b32 v3, v19, v43 offset0:68 offset1:84
	ds_write2_b32 v3, v20, v44 offset0:200 offset1:216
	ds_write2_b32 v2, v21, v45 offset0:76 offset1:92
	ds_write2_b32 v0, v34, v52 offset0:224 offset1:240
	ds_write2_b32 v3, v35, v53 offset0:100 offset1:116
	ds_write2_b32 v3, v36, v4 offset0:232 offset1:248
	ds_write2_b32 v2, v37, v5 offset0:108 offset1:124
	s_addc_u32 s7, s7, 0
	v_lshlrev_b32_e32 v0, 3, v98
	s_add_i32 s8, s8, s4
	v_mul_u32_u24_e32 v4, 0x210, v66
	s_add_i32 s5, s5, s19
	v_lshlrev_b32_e32 v5, 4, v98
	v_lshl_add_u64 v[2:3], s[6:7], 0, v[0:1]
	v_or_b32_e32 v0, s8, v66
	v_add3_u32 v4, s5, v4, v5
	s_mov_b32 s4, 0
	s_movk_i32 s5, 0x880
	s_waitcnt lgkmcnt(0)
	s_barrier

; __global__ void __launch_bounds__(256, 2) mega(P p, int ph_lo, int ph_hi, int coop) {
;   __shared__ __attribute__((aligned(16))) char lds[LDS_BYTES];
	.amdhsa_kernel _Z4mega1Piii
		.amdhsa_group_segment_fixed_size 68112
		.amdhsa_private_segment_fixed_size 0
		.amdhsa_kernarg_size 400
		.amdhsa_user_sgpr_count 2
		.amdhsa_user_sgpr_dispatch_ptr 0
		.amdhsa_user_sgpr_queue_ptr 0
		.amdhsa_user_sgpr_kernarg_segment_ptr 1
		.amdhsa_user_sgpr_dispatch_id 0
		.amdhsa_user_sgpr_kernarg_preload_length 0
		.amdhsa_user_sgpr_kernarg_preload_offset 0
		.amdhsa_user_sgpr_private_segment_size 0
		.amdhsa_uses_dynamic_stack 0
		.amdhsa_enable_private_segment 0
		.amdhsa_system_sgpr_workgroup_id_x 1
		.amdhsa_system_sgpr_workgroup_id_y 0
		.amdhsa_system_sgpr_workgroup_id_z 0
		.amdhsa_system_sgpr_workgroup_info 0
		.amdhsa_system_vgpr_workitem_id 2
		.amdhsa_next_free_vgpr 248
		.amdhsa_next_free_sgpr 102
		.amdhsa_accum_offset 248
		.amdhsa_reserve_vcc 1
		.amdhsa_float_round_mode_32 0
		.amdhsa_float_round_mode_16_64 0
		.amdhsa_float_denorm_mode_32 3
		.amdhsa_float_denorm_mode_16_64 3
		.amdhsa_dx10_clamp 1
		.amdhsa_ieee_mode 1
		.amdhsa_fp16_overflow 0
		.amdhsa_tg_split 0
		.amdhsa_exception_fp_ieee_invalid_op 0
		.amdhsa_exception_fp_denorm_src 0
		.amdhsa_exception_fp_ieee_div_zero 0
		.amdhsa_exception_fp_ieee_overflow 0
		.amdhsa_exception_fp_ieee_underflow 0
		.amdhsa_exception_fp_ieee_inexact 0
		.amdhsa_exception_int_div_zero 0
	.end_amdhsa_kernel

; __global__ void __launch_bounds__(256, 2) mega(P p, int ph_lo, int ph_hi, int coop) {
;   __shared__ __attribute__((aligned(16))) char lds[LDS_BYTES];
amdhsa.kernels:
  - .agpr_count:     0
    .args:
      - .offset:         0
        .size:           128
        .value_kind:     by_value
      - .offset:         128
        .size:           4
        .value_kind:     by_value
      - .offset:         132
        .size:           4
        .value_kind:     by_value
      - .offset:         136
        .size:           4
        .value_kind:     by_value
      - .offset:         144
        .size:           4
        .value_kind:     hidden_block_count_x
      - .offset:         148
        .size:           4
        .value_kind:     hidden_block_count_y
      - .offset:         152
        .size:           4
        .value_kind:     hidden_block_count_z
      - .offset:         156
        .size:           2
        .value_kind:     hidden_group_size_x
      - .offset:         158
        .size:           2
        .value_kind:     hidden_group_size_y
      - .offset:         160
        .size:           2
        .value_kind:     hidden_group_size_z
      - .offset:         162
        .size:           2
        .value_kind:     hidden_remainder_x
      - .offset:         164
        .size:           2
        .value_kind:     hidden_remainder_y
      - .offset:         166
        .size:           2
        .value_kind:     hidden_remainder_z
      - .offset:         184
        .size:           8
        .value_kind:     hidden_global_offset_x
      - .offset:         192
        .size:           8
        .value_kind:     hidden_global_offset_y
      - .offset:         200
        .size:           8
        .value_kind:     hidden_global_offset_z
      - .offset:         208
        .size:           2
        .value_kind:     hidden_grid_dims
      - .offset:         232
        .size:           8
        .value_kind:     hidden_multigrid_sync_arg
    .group_segment_fixed_size: 68112
    .kernarg_segment_align: 8
    .kernarg_segment_size: 400
    .language:       OpenCL C
    .language_version:
      - 2
      - 0
    .max_flat_workgroup_size: 256
    .name:           _Z4mega1Piii
    .private_segment_fixed_size: 0
    .sgpr_count:     108
    .sgpr_spill_count: 523
    .symbol:         _Z4mega1Piii.kd
    .uniform_work_group_size: 1
    .uses_dynamic_stack: false
    .vgpr_count:     248
    .vgpr_spill_count: 0
    .wavefront_size: 64
